# loop-edge edit: K-loop counter/base increments and exit compare moved from after the last barrier to before it (only the branch remains between barrier release and the next segment), all 7 GEMM loops
# baseline (speedup 1.0000x reference)
; #define PG8_STAGE(bufoff, gbase, voff) do { _Pragma("unroll") for (int _i = 0; _i < 2; ++_i) \
;         __builtin_amdgcn_global_load_lds((const unsigned*)((const char*)(gbase) + (voff)[_i]), (LAS unsigned*)(lds + (bufoff) + ldsw + _i * 8192), 16, 0, 0); } while (0)
; #define PG8_LDA(dst, b, h) do { _Pragma("unroll") for (int m = 0; m < 4; ++m) _Pragma("unroll") for (int k = 0; k < 2; ++k) dst[m][k] = *(const LAS bf16x8*)(lds + PG8_SA(b, h) + aoff + m * 2048 + k * 1024); } while (0)
; #define PG8_LDB(dst, b, h) do { _Pragma("unroll") for (int n = 0; n < 2; ++n) _Pragma("unroll") for (int k = 0; k < 2; ++k) dst[n][k] = *(const LAS bf16x8*)(lds + PG8_SB(b, h) + boff + n * 2048 + k * 1024); } while (0)
; #define PG8_WAIT_V(n) asm volatile("s_waitcnt vmcnt(" #n ")" ::: "memory")
; #define PG8_WAIT_L(n) asm volatile("s_waitcnt lgkmcnt(" #n ")" ::: "memory")
; #define PG8_BAR __builtin_amdgcn_s_barrier()
; #define PG8_SCHED __builtin_amdgcn_sched_barrier(0)
; template <class Epi, class Sched, bool I8 = false>
; __device__ __forceinline__ void gemm_phase(LAS unsigned char* lds, const Gemm g, const Sched& S, const Epi& E) {
;     ...
;             PG8_LDB(B0, 0, 0); PG8_LDB(B1, 0, 1); PG8_SCHED; PG8_LDA(At, 0, 0); PG8_STAGE(PG8_SA(1, 1), a1 + hstepA, voffA);
;             PG8_WAIT_V(8); PG8_WAIT_L(0); PG8_BAR; PG8_MMA(0, 0, At, B0); PG8_MMA(0, 1, At, B1); PG8_BAR; PG8_SCHED;
;             PG8_LDA(At, 0, 1); PG8_STAGE(PG8_SB(0, 0), b2, voffB); PG8_STAGE(PG8_SB(0, 1), b2 + hstepB, voffB); PG8_STAGE(PG8_SA(0, 0), a2, voffA);
;             PG8_WAIT_V(8); PG8_WAIT_L(0); PG8_BAR; PG8_MMA(1, 0, At, B0); PG8_MMA(1, 1, At, B1); PG8_BAR; PG8_SCHED;
.LBB0_1169:
	ds_read_b128 v[90:93], v169
	ds_read_b128 v[98:101], v169 offset:1024
	ds_read_b128 v[172:175], v169 offset:2048
	ds_read_b128 v[176:179], v169 offset:3072
	ds_read_b128 v[180:183], v170
	ds_read_b128 v[184:187], v170 offset:1024
	ds_read_b128 v[188:191], v170 offset:2048
	ds_read_b128 v[192:195], v170 offset:3072
	s_add_u32 s22, s20, 0x4000
	s_addc_u32 s23, s21, 0
	s_cmp_eq_u32 s53, 28
	s_cselect_b32 s26, s49, s22
	s_cselect_b32 s27, s13, s23
	s_cselect_b32 s24, s50, s51
	s_cselect_b32 s25, s11, s52
	s_add_u32 s22, s26, 0x8000
	s_addc_u32 s23, s27, 0
	s_sub_u32 s98, s20, 0x4000
	s_subb_u32 s99, s21, 0
	s_mov_b32 m0, s43
	s_nop 0
	global_load_lds_dwordx4 v144, s[98:99]
	s_mov_b32 m0, s44
	s_nop 0
	global_load_lds_dwordx4 v140, s[98:99]
	s_add_i32 m0, s36, 0xc000
	ds_read_b128 v[196:199], v171
	ds_read_b128 v[200:203], v171 offset:1024
	ds_read_b128 v[204:207], v171 offset:2048
	ds_read_b128 v[208:211], v171 offset:3072
	ds_read_b128 v[212:215], v171 offset:4096
	ds_read_b128 v[216:219], v171 offset:5120
	ds_read_b128 v[220:223], v171 offset:6144
	ds_read_b128 v[224:227], v171 offset:7168
	global_load_lds_dwordx4 v148, s[20:21]
	s_add_i32 m0, s36, 0xe000
	s_nop 0
	global_load_lds_dwordx4 v150, s[20:21]
	s_waitcnt vmcnt(8)
	s_waitcnt lgkmcnt(0)
	s_barrier
	s_waitcnt lgkmcnt(0)
	v_mfma_i32_16x16x64_i8 v[134:137], v[90:93], v[196:199], v[134:137]
	v_mfma_i32_16x16x64_i8 v[130:133], v[172:175], v[196:199], v[130:133]
	v_mfma_i32_16x16x64_i8 v[118:121], v[90:93], v[204:207], v[118:121]
	v_mfma_i32_16x16x64_i8 v[114:117], v[172:175], v[204:207], v[114:117]
	v_mfma_i32_16x16x64_i8 v[102:105], v[90:93], v[212:215], v[102:105]
	v_mfma_i32_16x16x64_i8 v[94:97], v[172:175], v[212:215], v[94:97]
	v_mfma_i32_16x16x64_i8 v[78:81], v[90:93], v[220:223], v[78:81]
	v_mfma_i32_16x16x64_i8 v[74:77], v[172:175], v[220:223], v[74:77]
	v_mfma_i32_16x16x64_i8 v[134:137], v[98:101], v[200:203], v[134:137]
	v_mfma_i32_16x16x64_i8 v[130:133], v[176:179], v[200:203], v[130:133]
	v_mfma_i32_16x16x64_i8 v[118:121], v[98:101], v[208:211], v[118:121]
	v_mfma_i32_16x16x64_i8 v[114:117], v[176:179], v[208:211], v[114:117]
	v_mfma_i32_16x16x64_i8 v[102:105], v[98:101], v[216:219], v[102:105]
	v_mfma_i32_16x16x64_i8 v[94:97], v[176:179], v[216:219], v[94:97]
	v_mfma_i32_16x16x64_i8 v[78:81], v[98:101], v[224:227], v[78:81]
	v_mfma_i32_16x16x64_i8 v[74:77], v[176:179], v[224:227], v[74:77]
	v_mfma_i32_16x16x64_i8 v[126:129], v[180:183], v[196:199], v[126:129]
	v_mfma_i32_16x16x64_i8 v[122:125], v[188:191], v[196:199], v[122:125]
	v_mfma_i32_16x16x64_i8 v[110:113], v[180:183], v[204:207], v[110:113]
	v_mfma_i32_16x16x64_i8 v[106:109], v[188:191], v[204:207], v[106:109]
	v_mfma_i32_16x16x64_i8 v[86:89], v[180:183], v[212:215], v[86:89]
	v_mfma_i32_16x16x64_i8 v[82:85], v[188:191], v[212:215], v[82:85]
	v_mfma_i32_16x16x64_i8 v[70:73], v[180:183], v[220:223], v[70:73]
	v_mfma_i32_16x16x64_i8 v[66:69], v[188:191], v[220:223], v[66:69]
	v_mfma_i32_16x16x64_i8 v[126:129], v[184:187], v[200:203], v[126:129]
	v_mfma_i32_16x16x64_i8 v[122:125], v[192:195], v[200:203], v[122:125]
	v_mfma_i32_16x16x64_i8 v[110:113], v[184:187], v[208:211], v[110:113]
	v_mfma_i32_16x16x64_i8 v[106:109], v[192:195], v[208:211], v[106:109]
	v_mfma_i32_16x16x64_i8 v[86:89], v[184:187], v[216:219], v[86:89]
	v_mfma_i32_16x16x64_i8 v[82:85], v[192:195], v[216:219], v[82:85]
	v_mfma_i32_16x16x64_i8 v[70:73], v[184:187], v[224:227], v[70:73]
	v_mfma_i32_16x16x64_i8 v[66:69], v[192:195], v[224:227], v[66:69]
	s_barrier
	s_add_i32 s54, s46, s33
	s_mov_b32 m0, s54
	ds_read_b128 v[196:199], v171 offset:16384
	ds_read_b128 v[200:203], v171 offset:17408
	ds_read_b128 v[204:207], v171 offset:18432
	ds_read_b128 v[208:211], v171 offset:19456
	ds_read_b128 v[212:215], v171 offset:20480
	ds_read_b128 v[216:219], v171 offset:21504
	ds_read_b128 v[220:223], v171 offset:22528
	ds_read_b128 v[224:227], v171 offset:23552
	global_load_lds_dwordx4 v142, s[24:25]
	s_add_i32 m0, s54, 0x2000
	s_add_u32 s54, s24, 0x4000
	s_addc_u32 s55, s25, 0
	s_add_i32 s56, s47, s33
	global_load_lds_dwordx4 v138, s[24:25]
	s_mov_b32 m0, s56
	s_nop 0
	global_load_lds_dwordx4 v142, s[54:55]
	s_add_i32 m0, s56, 0x2000
	s_nop 0
	global_load_lds_dwordx4 v138, s[54:55]
	s_waitcnt vmcnt(6)
	s_waitcnt lgkmcnt(0)
	s_barrier
	s_waitcnt lgkmcnt(0)
	v_mfma_i32_16x16x64_i8 v[62:65], v[90:93], v[196:199], v[62:65]
	v_mfma_i32_16x16x64_i8 v[58:61], v[172:175], v[196:199], v[58:61]
	v_mfma_i32_16x16x64_i8 v[46:49], v[90:93], v[204:207], v[46:49]
	v_mfma_i32_16x16x64_i8 v[42:45], v[172:175], v[204:207], v[42:45]
	v_mfma_i32_16x16x64_i8 v[30:33], v[90:93], v[212:215], v[30:33]
	v_mfma_i32_16x16x64_i8 v[26:29], v[172:175], v[212:215], v[26:29]
	v_mfma_i32_16x16x64_i8 v[14:17], v[90:93], v[220:223], v[14:17]
	v_mfma_i32_16x16x64_i8 v[10:13], v[172:175], v[220:223], v[10:13]
	v_mfma_i32_16x16x64_i8 v[62:65], v[98:101], v[200:203], v[62:65]
	v_mfma_i32_16x16x64_i8 v[58:61], v[176:179], v[200:203], v[58:61]
	v_mfma_i32_16x16x64_i8 v[46:49], v[98:101], v[208:211], v[46:49]
	v_mfma_i32_16x16x64_i8 v[42:45], v[176:179], v[208:211], v[42:45]
	v_mfma_i32_16x16x64_i8 v[30:33], v[98:101], v[216:219], v[30:33]
	v_mfma_i32_16x16x64_i8 v[26:29], v[176:179], v[216:219], v[26:29]
	v_mfma_i32_16x16x64_i8 v[14:17], v[98:101], v[224:227], v[14:17]
	v_mfma_i32_16x16x64_i8 v[10:13], v[176:179], v[224:227], v[10:13]
	v_mfma_i32_16x16x64_i8 v[54:57], v[180:183], v[196:199], v[54:57]
	v_mfma_i32_16x16x64_i8 v[50:53], v[188:191], v[196:199], v[50:53]
	v_mfma_i32_16x16x64_i8 v[38:41], v[180:183], v[204:207], v[38:41]
	v_mfma_i32_16x16x64_i8 v[34:37], v[188:191], v[204:207], v[34:37]
	v_mfma_i32_16x16x64_i8 v[22:25], v[180:183], v[212:215], v[22:25]
	v_mfma_i32_16x16x64_i8 v[18:21], v[188:191], v[212:215], v[18:21]
	v_mfma_i32_16x16x64_i8 v[6:9], v[180:183], v[220:223], v[6:9]
	v_mfma_i32_16x16x64_i8 v[2:5], v[188:191], v[220:223], v[2:5]
	v_mfma_i32_16x16x64_i8 v[54:57], v[184:187], v[200:203], v[54:57]
	v_mfma_i32_16x16x64_i8 v[50:53], v[192:195], v[200:203], v[50:53]
	v_mfma_i32_16x16x64_i8 v[38:41], v[184:187], v[208:211], v[38:41]
	v_mfma_i32_16x16x64_i8 v[34:37], v[192:195], v[208:211], v[34:37]
	v_mfma_i32_16x16x64_i8 v[22:25], v[184:187], v[216:219], v[22:25]
	v_mfma_i32_16x16x64_i8 v[18:21], v[192:195], v[216:219], v[18:21]
	v_mfma_i32_16x16x64_i8 v[6:9], v[184:187], v[224:227], v[6:9]
	v_mfma_i32_16x16x64_i8 v[2:5], v[192:195], v[224:227], v[2:5]
	s_barrier
; #define PG8_STAGE(bufoff, gbase, voff) do { _Pragma("unroll") for (int _i = 0; _i < 2; ++_i) \
;         __builtin_amdgcn_global_load_lds((const unsigned*)((const char*)(gbase) + (voff)[_i]), (LAS unsigned*)(lds + (bufoff) + ldsw + _i * 8192), 16, 0, 0); } while (0)
; #define PG8_LDA(dst, b, h) do { _Pragma("unroll") for (int m = 0; m < 4; ++m) _Pragma("unroll") for (int k = 0; k < 2; ++k) dst[m][k] = *(const LAS bf16x8*)(lds + PG8_SA(b, h) + aoff + m * 2048 + k * 1024); } while (0)
; #define PG8_LDB(dst, b, h) do { _Pragma("unroll") for (int n = 0; n < 2; ++n) _Pragma("unroll") for (int k = 0; k < 2; ++k) dst[n][k] = *(const LAS bf16x8*)(lds + PG8_SB(b, h) + boff + n * 2048 + k * 1024); } while (0)
; #define PG8_WAIT_V(n) asm volatile("s_waitcnt vmcnt(" #n ")" ::: "memory")
; #define PG8_WAIT_L(n) asm volatile("s_waitcnt lgkmcnt(" #n ")" ::: "memory")
; #define PG8_BAR __builtin_amdgcn_s_barrier()
; #define PG8_SCHED __builtin_amdgcn_sched_barrier(0)
; template <class Epi, class Sched, bool I8 = false>
; __device__ __forceinline__ void gemm_phase(LAS unsigned char* lds, const Gemm g, const Sched& S, const Epi& E) {
;     ...
;             PG8_LDB(B0, 1, 0); PG8_LDB(B1, 1, 1); PG8_SCHED; PG8_LDA(At, 1, 0); PG8_STAGE(PG8_SA(0, 1), a2 + hstepA, voffA);
;             PG8_WAIT_V(8); PG8_WAIT_L(0); PG8_BAR; PG8_MMA(0, 0, At, B0); PG8_MMA(0, 1, At, B1); PG8_BAR; PG8_SCHED;
;             PG8_LDA(At, 1, 1); PG8_STAGE(PG8_SB(1, 0), b3, voffB); PG8_STAGE(PG8_SB(1, 1), b3 + hstepB, voffB); PG8_STAGE(PG8_SA(1, 0), a3, voffA);
;             PG8_WAIT_V(8); PG8_WAIT_L(0); PG8_BAR; PG8_MMA(1, 0, At, B0); PG8_MMA(1, 1, At, B1); PG8_BAR; PG8_SCHED;
	s_add_i32 s54, 0, 0x18000
	v_add_u32_e32 v146, s54, v165
	s_add_i32 s55, 0, 0x1c000
	ds_read_b128 v[90:93], v146
	ds_read_b128 v[98:101], v146 offset:1024
	ds_read_b128 v[172:175], v146 offset:2048
	ds_read_b128 v[176:179], v146 offset:3072
	v_add_u32_e32 v146, s55, v165
	ds_read_b128 v[180:183], v146
	ds_read_b128 v[184:187], v146 offset:1024
	ds_read_b128 v[188:191], v146 offset:2048
	ds_read_b128 v[192:195], v146 offset:3072
	s_mov_b32 m0, s36
	s_nop 0
	global_load_lds_dwordx4 v144, s[26:27]
	s_mov_b32 m0, s37
	s_nop 0
	global_load_lds_dwordx4 v140, s[26:27]
	s_add_u32 s26, s26, 0x4000
	s_addc_u32 s27, s27, 0
	s_mov_b32 m0, s38
	ds_read_b128 v[196:199], v171 offset:32768
	ds_read_b128 v[200:203], v171 offset:33792
	ds_read_b128 v[204:207], v171 offset:34816
	ds_read_b128 v[208:211], v171 offset:35840
	ds_read_b128 v[212:215], v171 offset:36864
	ds_read_b128 v[216:219], v171 offset:37888
	ds_read_b128 v[220:223], v171 offset:38912
	ds_read_b128 v[224:227], v171 offset:39936
	global_load_lds_dwordx4 v144, s[26:27]
	s_mov_b32 m0, s39
	s_nop 0
	global_load_lds_dwordx4 v140, s[26:27]
	s_waitcnt vmcnt(8)
	s_waitcnt lgkmcnt(0)
	s_barrier
	s_waitcnt lgkmcnt(0)
	v_mfma_i32_16x16x64_i8 v[134:137], v[90:93], v[196:199], v[134:137]
	v_mfma_i32_16x16x64_i8 v[130:133], v[172:175], v[196:199], v[130:133]
	v_mfma_i32_16x16x64_i8 v[118:121], v[90:93], v[204:207], v[118:121]
	v_mfma_i32_16x16x64_i8 v[114:117], v[172:175], v[204:207], v[114:117]
	v_mfma_i32_16x16x64_i8 v[102:105], v[90:93], v[212:215], v[102:105]
	v_mfma_i32_16x16x64_i8 v[94:97], v[172:175], v[212:215], v[94:97]
	v_mfma_i32_16x16x64_i8 v[78:81], v[90:93], v[220:223], v[78:81]
	v_mfma_i32_16x16x64_i8 v[74:77], v[172:175], v[220:223], v[74:77]
	v_mfma_i32_16x16x64_i8 v[134:137], v[98:101], v[200:203], v[134:137]
	v_mfma_i32_16x16x64_i8 v[130:133], v[176:179], v[200:203], v[130:133]
	v_mfma_i32_16x16x64_i8 v[118:121], v[98:101], v[208:211], v[118:121]
	v_mfma_i32_16x16x64_i8 v[114:117], v[176:179], v[208:211], v[114:117]
	v_mfma_i32_16x16x64_i8 v[102:105], v[98:101], v[216:219], v[102:105]
	v_mfma_i32_16x16x64_i8 v[94:97], v[176:179], v[216:219], v[94:97]
	v_mfma_i32_16x16x64_i8 v[78:81], v[98:101], v[224:227], v[78:81]
	v_mfma_i32_16x16x64_i8 v[74:77], v[176:179], v[224:227], v[74:77]
	v_mfma_i32_16x16x64_i8 v[126:129], v[180:183], v[196:199], v[126:129]
	v_mfma_i32_16x16x64_i8 v[122:125], v[188:191], v[196:199], v[122:125]
	v_mfma_i32_16x16x64_i8 v[110:113], v[180:183], v[204:207], v[110:113]
	v_mfma_i32_16x16x64_i8 v[106:109], v[188:191], v[204:207], v[106:109]
	v_mfma_i32_16x16x64_i8 v[86:89], v[180:183], v[212:215], v[86:89]
	v_mfma_i32_16x16x64_i8 v[82:85], v[188:191], v[212:215], v[82:85]
	v_mfma_i32_16x16x64_i8 v[70:73], v[180:183], v[220:223], v[70:73]
	v_mfma_i32_16x16x64_i8 v[66:69], v[188:191], v[220:223], v[66:69]
	v_mfma_i32_16x16x64_i8 v[126:129], v[184:187], v[200:203], v[126:129]
	v_mfma_i32_16x16x64_i8 v[122:125], v[192:195], v[200:203], v[122:125]
	v_mfma_i32_16x16x64_i8 v[110:113], v[184:187], v[208:211], v[110:113]
	v_mfma_i32_16x16x64_i8 v[106:109], v[192:195], v[208:211], v[106:109]
	v_mfma_i32_16x16x64_i8 v[86:89], v[184:187], v[216:219], v[86:89]
	v_mfma_i32_16x16x64_i8 v[82:85], v[192:195], v[216:219], v[82:85]
	v_mfma_i32_16x16x64_i8 v[70:73], v[184:187], v[224:227], v[70:73]
	v_mfma_i32_16x16x64_i8 v[66:69], v[192:195], v[224:227], v[66:69]
	s_barrier
	s_add_u32 s26, s24, 0x8000
	s_addc_u32 s27, s25, 0
	s_add_i32 s54, s54, s33
	s_mov_b32 m0, s54
	ds_read_b128 v[196:199], v171 offset:49152
	ds_read_b128 v[200:203], v171 offset:50176
	ds_read_b128 v[204:207], v171 offset:51200
	ds_read_b128 v[208:211], v171 offset:52224
	ds_read_b128 v[212:215], v171 offset:53248
	ds_read_b128 v[216:219], v171 offset:54272
	ds_read_b128 v[220:223], v171 offset:55296
	ds_read_b128 v[224:227], v171 offset:56320
	global_load_lds_dwordx4 v142, s[26:27]
	s_add_i32 m0, s54, 0x2000
	s_add_u32 s24, s24, 0xc000
	v_lshl_add_u64 v[158:159], s[26:27], 0, v[138:139]
	s_addc_u32 s25, s25, 0
	s_add_i32 s26, s55, s33
	global_load_lds_dwordx4 v[158:159], off
	s_mov_b32 m0, s26
	s_nop 0
	global_load_lds_dwordx4 v142, s[24:25]
	s_add_i32 m0, s26, 0x2000
	s_nop 0
	global_load_lds_dwordx4 v138, s[24:25]
	s_waitcnt vmcnt(6)
	s_waitcnt lgkmcnt(0)
	s_barrier
	s_waitcnt lgkmcnt(0)
	v_mfma_i32_16x16x64_i8 v[62:65], v[90:93], v[196:199], v[62:65]
	v_mfma_i32_16x16x64_i8 v[58:61], v[172:175], v[196:199], v[58:61]
	v_mfma_i32_16x16x64_i8 v[46:49], v[90:93], v[204:207], v[46:49]
	v_mfma_i32_16x16x64_i8 v[42:45], v[172:175], v[204:207], v[42:45]
	v_mfma_i32_16x16x64_i8 v[30:33], v[90:93], v[212:215], v[30:33]
	v_mfma_i32_16x16x64_i8 v[26:29], v[172:175], v[212:215], v[26:29]
	v_mfma_i32_16x16x64_i8 v[14:17], v[90:93], v[220:223], v[14:17]
	v_mfma_i32_16x16x64_i8 v[10:13], v[172:175], v[220:223], v[10:13]
	v_mfma_i32_16x16x64_i8 v[62:65], v[98:101], v[200:203], v[62:65]
	v_mfma_i32_16x16x64_i8 v[58:61], v[176:179], v[200:203], v[58:61]
	v_mfma_i32_16x16x64_i8 v[46:49], v[98:101], v[208:211], v[46:49]
	v_mfma_i32_16x16x64_i8 v[42:45], v[176:179], v[208:211], v[42:45]
	v_mfma_i32_16x16x64_i8 v[30:33], v[98:101], v[216:219], v[30:33]
	v_mfma_i32_16x16x64_i8 v[26:29], v[176:179], v[216:219], v[26:29]
	v_mfma_i32_16x16x64_i8 v[14:17], v[98:101], v[224:227], v[14:17]
	v_mfma_i32_16x16x64_i8 v[10:13], v[176:179], v[224:227], v[10:13]
	v_mfma_i32_16x16x64_i8 v[54:57], v[180:183], v[196:199], v[54:57]
	v_mfma_i32_16x16x64_i8 v[50:53], v[188:191], v[196:199], v[50:53]
	v_mfma_i32_16x16x64_i8 v[38:41], v[180:183], v[204:207], v[38:41]
	v_mfma_i32_16x16x64_i8 v[34:37], v[188:191], v[204:207], v[34:37]
	v_mfma_i32_16x16x64_i8 v[22:25], v[180:183], v[212:215], v[22:25]
	v_mfma_i32_16x16x64_i8 v[18:21], v[188:191], v[212:215], v[18:21]
	v_mfma_i32_16x16x64_i8 v[6:9], v[180:183], v[220:223], v[6:9]
	v_mfma_i32_16x16x64_i8 v[2:5], v[188:191], v[220:223], v[2:5]
	v_mfma_i32_16x16x64_i8 v[54:57], v[184:187], v[200:203], v[54:57]
	v_mfma_i32_16x16x64_i8 v[50:53], v[192:195], v[200:203], v[50:53]
	v_mfma_i32_16x16x64_i8 v[38:41], v[184:187], v[208:211], v[38:41]
	v_mfma_i32_16x16x64_i8 v[34:37], v[192:195], v[208:211], v[34:37]
	v_mfma_i32_16x16x64_i8 v[22:25], v[184:187], v[216:219], v[22:25]
	v_mfma_i32_16x16x64_i8 v[18:21], v[192:195], v[216:219], v[18:21]
	v_mfma_i32_16x16x64_i8 v[6:9], v[184:187], v[224:227], v[6:9]
	v_mfma_i32_16x16x64_i8 v[2:5], v[192:195], v[224:227], v[2:5]
	s_add_i32 s53, s53, 2
	s_add_u32 s20, s20, 0x10000
	s_addc_u32 s21, s21, 0
	s_add_u32 s51, s51, 0x10000
	s_addc_u32 s52, s52, 0
	s_cmp_gt_u32 s53, 29
	s_barrier
	s_cbranch_scc0 .LBB0_1169
	s_and_b64 vcc, exec, s[8:9]
	s_cbranch_vccz .LBB0_1172
	s_barrier

; #define PG8_STAGE(bufoff, gbase, voff) do { _Pragma("unroll") for (int _i = 0; _i < 2; ++_i) \
;         __builtin_amdgcn_global_load_lds((const unsigned*)((const char*)(gbase) + (voff)[_i]), (LAS unsigned*)(lds + (bufoff) + ldsw + _i * 8192), 16, 0, 0); } while (0)
; #define PG8_LDA(dst, b, h) do { _Pragma("unroll") for (int m = 0; m < 4; ++m) _Pragma("unroll") for (int k = 0; k < 2; ++k) dst[m][k] = *(const LAS bf16x8*)(lds + PG8_SA(b, h) + aoff + m * 2048 + k * 1024); } while (0)
; #define PG8_LDB(dst, b, h) do { _Pragma("unroll") for (int n = 0; n < 2; ++n) _Pragma("unroll") for (int k = 0; k < 2; ++k) dst[n][k] = *(const LAS bf16x8*)(lds + PG8_SB(b, h) + boff + n * 2048 + k * 1024); } while (0)
; #define PG8_WAIT_V(n) asm volatile("s_waitcnt vmcnt(" #n ")" ::: "memory")
; #define PG8_WAIT_L(n) asm volatile("s_waitcnt lgkmcnt(" #n ")" ::: "memory")
; #define PG8_BAR __builtin_amdgcn_s_barrier()
; #define PG8_SCHED __builtin_amdgcn_sched_barrier(0)
; template <class Epi, class Sched, bool I8 = false>
; __device__ __forceinline__ void gemm_phase(LAS unsigned char* lds, const Gemm g, const Sched& S, const Epi& E) {
;     ...
;             PG8_LDB(B0, 0, 0); PG8_LDB(B1, 0, 1); PG8_SCHED; PG8_LDA(At, 0, 0); PG8_STAGE(PG8_SA(1, 1), a1 + hstepA, voffA);
;             PG8_WAIT_V(8); PG8_WAIT_L(0); PG8_BAR; PG8_MMA(0, 0, At, B0); PG8_MMA(0, 1, At, B1); PG8_BAR; PG8_SCHED;
;             PG8_LDA(At, 0, 1); PG8_STAGE(PG8_SB(0, 0), b2, voffB); PG8_STAGE(PG8_SB(0, 1), b2 + hstepB, voffB); PG8_STAGE(PG8_SA(0, 0), a2, voffA);
;             PG8_WAIT_V(8); PG8_WAIT_L(0); PG8_BAR; PG8_MMA(1, 0, At, B0); PG8_MMA(1, 1, At, B1); PG8_BAR; PG8_SCHED;
.LBB0_1393:
	ds_read_b128 v[66:69], v180
	ds_read_b128 v[70:73], v180 offset:1024
	ds_read_b128 v[74:77], v180 offset:2048
	ds_read_b128 v[78:81], v180 offset:3072
	ds_read_b128 v[146:149], v181
	ds_read_b128 v[150:153], v181 offset:1024
	ds_read_b128 v[174:177], v181 offset:2048
	ds_read_b128 v[184:187], v181 offset:3072
	s_add_u32 s20, s18, 0x4000
	s_addc_u32 s21, s19, 0
	s_cmpk_eq_i32 s49, 0x52
	s_cselect_b32 s24, s0, s20
	s_cselect_b32 s25, s1, s21
	s_cselect_b32 s22, s16, s47
	s_cselect_b32 s23, s17, s48
	s_add_u32 s20, s24, 0x8000
	s_addc_u32 s21, s25, 0
	s_sub_u32 s98, s18, 0x4000
	s_subb_u32 s99, s19, 0
	s_mov_b32 m0, s37
	s_nop 0
	global_load_lds_dwordx4 v156, s[98:99]
	s_mov_b32 m0, s38
	s_nop 0
	global_load_lds_dwordx4 v160, s[98:99]
	s_add_i32 m0, s31, 0xc000
	ds_read_b128 v[188:191], v182
	ds_read_b128 v[192:195], v182 offset:1024
	ds_read_b128 v[196:199], v182 offset:2048
	ds_read_b128 v[200:203], v182 offset:3072
	ds_read_b128 v[204:207], v182 offset:4096
	ds_read_b128 v[208:211], v182 offset:5120
	ds_read_b128 v[212:215], v182 offset:6144
	ds_read_b128 v[216:219], v182 offset:7168
	global_load_lds_dwordx4 v166, s[18:19]
	s_add_i32 m0, s31, 0xe000
	s_nop 0
	global_load_lds_dwordx4 v168, s[18:19]
	s_waitcnt vmcnt(8)
	s_waitcnt lgkmcnt(0)
	s_barrier
	s_waitcnt lgkmcnt(0)
	v_mfma_i32_16x16x64_i8 v[142:145], v[66:69], v[188:191], v[142:145]
	v_mfma_i32_16x16x64_i8 v[138:141], v[74:77], v[188:191], v[138:141]
	v_mfma_i32_16x16x64_i8 v[126:129], v[66:69], v[196:199], v[126:129]
	v_mfma_i32_16x16x64_i8 v[122:125], v[74:77], v[196:199], v[122:125]
	v_mfma_i32_16x16x64_i8 v[110:113], v[66:69], v[204:207], v[110:113]
	v_mfma_i32_16x16x64_i8 v[106:109], v[74:77], v[204:207], v[106:109]
	v_mfma_i32_16x16x64_i8 v[94:97], v[66:69], v[212:215], v[94:97]
	v_mfma_i32_16x16x64_i8 v[90:93], v[74:77], v[212:215], v[90:93]
	v_mfma_i32_16x16x64_i8 v[142:145], v[70:73], v[192:195], v[142:145]
	v_mfma_i32_16x16x64_i8 v[138:141], v[78:81], v[192:195], v[138:141]
	v_mfma_i32_16x16x64_i8 v[126:129], v[70:73], v[200:203], v[126:129]
	v_mfma_i32_16x16x64_i8 v[122:125], v[78:81], v[200:203], v[122:125]
	v_mfma_i32_16x16x64_i8 v[110:113], v[70:73], v[208:211], v[110:113]
	v_mfma_i32_16x16x64_i8 v[106:109], v[78:81], v[208:211], v[106:109]
	v_mfma_i32_16x16x64_i8 v[94:97], v[70:73], v[216:219], v[94:97]
	v_mfma_i32_16x16x64_i8 v[90:93], v[78:81], v[216:219], v[90:93]
	v_mfma_i32_16x16x64_i8 v[134:137], v[146:149], v[188:191], v[134:137]
	v_mfma_i32_16x16x64_i8 v[130:133], v[174:177], v[188:191], v[130:133]
	v_mfma_i32_16x16x64_i8 v[118:121], v[146:149], v[196:199], v[118:121]
	v_mfma_i32_16x16x64_i8 v[114:117], v[174:177], v[196:199], v[114:117]
	v_mfma_i32_16x16x64_i8 v[102:105], v[146:149], v[204:207], v[102:105]
	v_mfma_i32_16x16x64_i8 v[98:101], v[174:177], v[204:207], v[98:101]
	v_mfma_i32_16x16x64_i8 v[86:89], v[146:149], v[212:215], v[86:89]
	v_mfma_i32_16x16x64_i8 v[82:85], v[174:177], v[212:215], v[82:85]
	v_mfma_i32_16x16x64_i8 v[134:137], v[150:153], v[192:195], v[134:137]
	v_mfma_i32_16x16x64_i8 v[130:133], v[184:187], v[192:195], v[130:133]
	v_mfma_i32_16x16x64_i8 v[118:121], v[150:153], v[200:203], v[118:121]
	v_mfma_i32_16x16x64_i8 v[114:117], v[184:187], v[200:203], v[114:117]
	v_mfma_i32_16x16x64_i8 v[102:105], v[150:153], v[208:211], v[102:105]
	v_mfma_i32_16x16x64_i8 v[98:101], v[184:187], v[208:211], v[98:101]
	v_mfma_i32_16x16x64_i8 v[86:89], v[150:153], v[216:219], v[86:89]
	v_mfma_i32_16x16x64_i8 v[82:85], v[184:187], v[216:219], v[82:85]
	s_barrier
	s_add_i32 s50, s41, s30
	s_mov_b32 m0, s50
	ds_read_b128 v[188:191], v182 offset:16384
	ds_read_b128 v[192:195], v182 offset:17408
	ds_read_b128 v[196:199], v182 offset:18432
	ds_read_b128 v[200:203], v182 offset:19456
	ds_read_b128 v[204:207], v182 offset:20480
	ds_read_b128 v[208:211], v182 offset:21504
	ds_read_b128 v[212:215], v182 offset:22528
	ds_read_b128 v[216:219], v182 offset:23552
	global_load_lds_dwordx4 v158, s[22:23]
	s_add_i32 m0, s50, 0x2000
	s_add_u32 s50, s22, 0x4000
	s_addc_u32 s51, s23, 0
	s_add_i32 s52, s42, s30
	global_load_lds_dwordx4 v162, s[22:23]
	s_mov_b32 m0, s52
	s_nop 0
	global_load_lds_dwordx4 v158, s[50:51]
	s_add_i32 m0, s52, 0x2000
	s_nop 0
	global_load_lds_dwordx4 v162, s[50:51]
	s_waitcnt vmcnt(6)
	s_waitcnt lgkmcnt(0)
	s_barrier
	s_waitcnt lgkmcnt(0)
	v_mfma_i32_16x16x64_i8 v[62:65], v[66:69], v[188:191], v[62:65]
	v_mfma_i32_16x16x64_i8 v[58:61], v[74:77], v[188:191], v[58:61]
	v_mfma_i32_16x16x64_i8 v[46:49], v[66:69], v[196:199], v[46:49]
	v_mfma_i32_16x16x64_i8 v[42:45], v[74:77], v[196:199], v[42:45]
	v_mfma_i32_16x16x64_i8 v[30:33], v[66:69], v[204:207], v[30:33]
	v_mfma_i32_16x16x64_i8 v[26:29], v[74:77], v[204:207], v[26:29]
	v_mfma_i32_16x16x64_i8 v[14:17], v[66:69], v[212:215], v[14:17]
	v_mfma_i32_16x16x64_i8 v[10:13], v[74:77], v[212:215], v[10:13]
	v_mfma_i32_16x16x64_i8 v[62:65], v[70:73], v[192:195], v[62:65]
	v_mfma_i32_16x16x64_i8 v[58:61], v[78:81], v[192:195], v[58:61]
	v_mfma_i32_16x16x64_i8 v[46:49], v[70:73], v[200:203], v[46:49]
	v_mfma_i32_16x16x64_i8 v[42:45], v[78:81], v[200:203], v[42:45]
	v_mfma_i32_16x16x64_i8 v[30:33], v[70:73], v[208:211], v[30:33]
	v_mfma_i32_16x16x64_i8 v[26:29], v[78:81], v[208:211], v[26:29]
	v_mfma_i32_16x16x64_i8 v[14:17], v[70:73], v[216:219], v[14:17]
	v_mfma_i32_16x16x64_i8 v[10:13], v[78:81], v[216:219], v[10:13]
	v_mfma_i32_16x16x64_i8 v[54:57], v[146:149], v[188:191], v[54:57]
	v_mfma_i32_16x16x64_i8 v[50:53], v[174:177], v[188:191], v[50:53]
	v_mfma_i32_16x16x64_i8 v[38:41], v[146:149], v[196:199], v[38:41]
	v_mfma_i32_16x16x64_i8 v[34:37], v[174:177], v[196:199], v[34:37]
	v_mfma_i32_16x16x64_i8 v[22:25], v[146:149], v[204:207], v[22:25]
	v_mfma_i32_16x16x64_i8 v[18:21], v[174:177], v[204:207], v[18:21]
	v_mfma_i32_16x16x64_i8 v[6:9], v[146:149], v[212:215], v[6:9]
	v_mfma_i32_16x16x64_i8 v[2:5], v[174:177], v[212:215], v[2:5]
	v_mfma_i32_16x16x64_i8 v[54:57], v[150:153], v[192:195], v[54:57]
	v_mfma_i32_16x16x64_i8 v[50:53], v[184:187], v[192:195], v[50:53]
	v_mfma_i32_16x16x64_i8 v[38:41], v[150:153], v[200:203], v[38:41]
	v_mfma_i32_16x16x64_i8 v[34:37], v[184:187], v[200:203], v[34:37]
	v_mfma_i32_16x16x64_i8 v[22:25], v[150:153], v[208:211], v[22:25]
	v_mfma_i32_16x16x64_i8 v[18:21], v[184:187], v[208:211], v[18:21]
	v_mfma_i32_16x16x64_i8 v[6:9], v[150:153], v[216:219], v[6:9]
	v_mfma_i32_16x16x64_i8 v[2:5], v[184:187], v[216:219], v[2:5]
	s_barrier
; #define PG8_STAGE(bufoff, gbase, voff) do { _Pragma("unroll") for (int _i = 0; _i < 2; ++_i) \
;         __builtin_amdgcn_global_load_lds((const unsigned*)((const char*)(gbase) + (voff)[_i]), (LAS unsigned*)(lds + (bufoff) + ldsw + _i * 8192), 16, 0, 0); } while (0)
; #define PG8_LDA(dst, b, h) do { _Pragma("unroll") for (int m = 0; m < 4; ++m) _Pragma("unroll") for (int k = 0; k < 2; ++k) dst[m][k] = *(const LAS bf16x8*)(lds + PG8_SA(b, h) + aoff + m * 2048 + k * 1024); } while (0)
; #define PG8_LDB(dst, b, h) do { _Pragma("unroll") for (int n = 0; n < 2; ++n) _Pragma("unroll") for (int k = 0; k < 2; ++k) dst[n][k] = *(const LAS bf16x8*)(lds + PG8_SB(b, h) + boff + n * 2048 + k * 1024); } while (0)
; #define PG8_WAIT_V(n) asm volatile("s_waitcnt vmcnt(" #n ")" ::: "memory")
; #define PG8_WAIT_L(n) asm volatile("s_waitcnt lgkmcnt(" #n ")" ::: "memory")
; #define PG8_BAR __builtin_amdgcn_s_barrier()
; #define PG8_SCHED __builtin_amdgcn_sched_barrier(0)
; template <class Epi, class Sched, bool I8 = false>
; __device__ __forceinline__ void gemm_phase(LAS unsigned char* lds, const Gemm g, const Sched& S, const Epi& E) {
;     ...
;             PG8_LDB(B0, 1, 0); PG8_LDB(B1, 1, 1); PG8_SCHED; PG8_LDA(At, 1, 0); PG8_STAGE(PG8_SA(0, 1), a2 + hstepA, voffA);
;             PG8_WAIT_V(8); PG8_WAIT_L(0); PG8_BAR; PG8_MMA(0, 0, At, B0); PG8_MMA(0, 1, At, B1); PG8_BAR; PG8_SCHED;
;             PG8_LDA(At, 1, 1); PG8_STAGE(PG8_SB(1, 0), b3, voffB); PG8_STAGE(PG8_SB(1, 1), b3 + hstepB, voffB); PG8_STAGE(PG8_SA(1, 0), a3, voffA);
;             PG8_WAIT_V(8); PG8_WAIT_L(0); PG8_BAR; PG8_MMA(1, 0, At, B0); PG8_MMA(1, 1, At, B1); PG8_BAR; PG8_SCHED;
	s_add_i32 s50, 0, 0x18000
	s_add_i32 s51, 0, 0x1c000
	v_add_u32_e32 v78, s50, v178
	v_add_u32_e32 v164, s51, v178
	ds_read_b128 v[66:69], v78
	ds_read_b128 v[70:73], v78 offset:1024
	ds_read_b128 v[74:77], v78 offset:2048
	ds_read_b128 v[78:81], v78 offset:3072
	ds_read_b128 v[146:149], v164
	ds_read_b128 v[150:153], v164 offset:1024
	ds_read_b128 v[174:177], v164 offset:2048
	ds_read_b128 v[184:187], v164 offset:3072
	s_mov_b32 m0, s31
	s_nop 0
	global_load_lds_dwordx4 v156, s[24:25]
	s_mov_b32 m0, s33
	s_nop 0
	global_load_lds_dwordx4 v160, s[24:25]
	s_add_u32 s24, s24, 0x4000
	s_addc_u32 s25, s25, 0
	s_mov_b32 m0, s34
	ds_read_b128 v[188:191], v182 offset:32768
	ds_read_b128 v[192:195], v182 offset:33792
	ds_read_b128 v[196:199], v182 offset:34816
	ds_read_b128 v[200:203], v182 offset:35840
	ds_read_b128 v[204:207], v182 offset:36864
	ds_read_b128 v[208:211], v182 offset:37888
	ds_read_b128 v[212:215], v182 offset:38912
	ds_read_b128 v[216:219], v182 offset:39936
	global_load_lds_dwordx4 v156, s[24:25]
	s_mov_b32 m0, s35
	s_nop 0
	global_load_lds_dwordx4 v160, s[24:25]
	s_waitcnt vmcnt(8)
	s_waitcnt lgkmcnt(0)
	s_barrier
	s_waitcnt lgkmcnt(0)
	v_mfma_i32_16x16x64_i8 v[142:145], v[66:69], v[188:191], v[142:145]
	v_mfma_i32_16x16x64_i8 v[138:141], v[74:77], v[188:191], v[138:141]
	v_mfma_i32_16x16x64_i8 v[126:129], v[66:69], v[196:199], v[126:129]
	v_mfma_i32_16x16x64_i8 v[122:125], v[74:77], v[196:199], v[122:125]
	v_mfma_i32_16x16x64_i8 v[110:113], v[66:69], v[204:207], v[110:113]
	v_mfma_i32_16x16x64_i8 v[106:109], v[74:77], v[204:207], v[106:109]
	v_mfma_i32_16x16x64_i8 v[94:97], v[66:69], v[212:215], v[94:97]
	v_mfma_i32_16x16x64_i8 v[90:93], v[74:77], v[212:215], v[90:93]
	v_mfma_i32_16x16x64_i8 v[142:145], v[70:73], v[192:195], v[142:145]
	v_mfma_i32_16x16x64_i8 v[138:141], v[78:81], v[192:195], v[138:141]
	v_mfma_i32_16x16x64_i8 v[126:129], v[70:73], v[200:203], v[126:129]
	v_mfma_i32_16x16x64_i8 v[122:125], v[78:81], v[200:203], v[122:125]
	v_mfma_i32_16x16x64_i8 v[110:113], v[70:73], v[208:211], v[110:113]
	v_mfma_i32_16x16x64_i8 v[106:109], v[78:81], v[208:211], v[106:109]
	v_mfma_i32_16x16x64_i8 v[94:97], v[70:73], v[216:219], v[94:97]
	v_mfma_i32_16x16x64_i8 v[90:93], v[78:81], v[216:219], v[90:93]
	v_mfma_i32_16x16x64_i8 v[134:137], v[146:149], v[188:191], v[134:137]
	v_mfma_i32_16x16x64_i8 v[130:133], v[174:177], v[188:191], v[130:133]
	v_mfma_i32_16x16x64_i8 v[118:121], v[146:149], v[196:199], v[118:121]
	v_mfma_i32_16x16x64_i8 v[114:117], v[174:177], v[196:199], v[114:117]
	v_mfma_i32_16x16x64_i8 v[102:105], v[146:149], v[204:207], v[102:105]
	v_mfma_i32_16x16x64_i8 v[98:101], v[174:177], v[204:207], v[98:101]
	v_mfma_i32_16x16x64_i8 v[86:89], v[146:149], v[212:215], v[86:89]
	v_mfma_i32_16x16x64_i8 v[82:85], v[174:177], v[212:215], v[82:85]
	v_mfma_i32_16x16x64_i8 v[134:137], v[150:153], v[192:195], v[134:137]
	v_mfma_i32_16x16x64_i8 v[130:133], v[184:187], v[192:195], v[130:133]
	v_mfma_i32_16x16x64_i8 v[118:121], v[150:153], v[200:203], v[118:121]
	v_mfma_i32_16x16x64_i8 v[114:117], v[184:187], v[200:203], v[114:117]
	v_mfma_i32_16x16x64_i8 v[102:105], v[150:153], v[208:211], v[102:105]
	v_mfma_i32_16x16x64_i8 v[98:101], v[184:187], v[208:211], v[98:101]
	v_mfma_i32_16x16x64_i8 v[86:89], v[150:153], v[216:219], v[86:89]
	v_mfma_i32_16x16x64_i8 v[82:85], v[184:187], v[216:219], v[82:85]
	s_barrier
	s_add_u32 s24, s22, 0x8000
	s_addc_u32 s25, s23, 0
	s_add_i32 s50, s50, s30
	s_mov_b32 m0, s50
	ds_read_b128 v[188:191], v182 offset:49152
	ds_read_b128 v[192:195], v182 offset:50176
	ds_read_b128 v[196:199], v182 offset:51200
	ds_read_b128 v[200:203], v182 offset:52224
	ds_read_b128 v[204:207], v182 offset:53248
	ds_read_b128 v[208:211], v182 offset:54272
	ds_read_b128 v[212:215], v182 offset:55296
	ds_read_b128 v[216:219], v182 offset:56320
	global_load_lds_dwordx4 v158, s[24:25]
	s_add_i32 m0, s50, 0x2000
	s_add_u32 s22, s22, 0xc000
	v_lshl_add_u64 v[220:221], s[24:25], 0, v[162:163]
	s_addc_u32 s23, s23, 0
	s_add_i32 s24, s51, s30
	global_load_lds_dwordx4 v[220:221], off
	s_mov_b32 m0, s24
	s_nop 0
	global_load_lds_dwordx4 v158, s[22:23]
	s_add_i32 m0, s24, 0x2000
	s_nop 0
	global_load_lds_dwordx4 v162, s[22:23]
	s_waitcnt vmcnt(6)
	s_waitcnt lgkmcnt(0)
	s_barrier
	s_waitcnt lgkmcnt(0)
	v_mfma_i32_16x16x64_i8 v[62:65], v[66:69], v[188:191], v[62:65]
	v_mfma_i32_16x16x64_i8 v[58:61], v[74:77], v[188:191], v[58:61]
	v_mfma_i32_16x16x64_i8 v[46:49], v[66:69], v[196:199], v[46:49]
	v_mfma_i32_16x16x64_i8 v[42:45], v[74:77], v[196:199], v[42:45]
	v_mfma_i32_16x16x64_i8 v[30:33], v[66:69], v[204:207], v[30:33]
	v_mfma_i32_16x16x64_i8 v[26:29], v[74:77], v[204:207], v[26:29]
	v_mfma_i32_16x16x64_i8 v[14:17], v[66:69], v[212:215], v[14:17]
	v_mfma_i32_16x16x64_i8 v[10:13], v[74:77], v[212:215], v[10:13]
	v_mfma_i32_16x16x64_i8 v[62:65], v[70:73], v[192:195], v[62:65]
	v_mfma_i32_16x16x64_i8 v[58:61], v[78:81], v[192:195], v[58:61]
	v_mfma_i32_16x16x64_i8 v[46:49], v[70:73], v[200:203], v[46:49]
	v_mfma_i32_16x16x64_i8 v[42:45], v[78:81], v[200:203], v[42:45]
	v_mfma_i32_16x16x64_i8 v[30:33], v[70:73], v[208:211], v[30:33]
	v_mfma_i32_16x16x64_i8 v[26:29], v[78:81], v[208:211], v[26:29]
	v_mfma_i32_16x16x64_i8 v[14:17], v[70:73], v[216:219], v[14:17]
	v_mfma_i32_16x16x64_i8 v[10:13], v[78:81], v[216:219], v[10:13]
	v_mfma_i32_16x16x64_i8 v[54:57], v[146:149], v[188:191], v[54:57]
	v_mfma_i32_16x16x64_i8 v[50:53], v[174:177], v[188:191], v[50:53]
	v_mfma_i32_16x16x64_i8 v[38:41], v[146:149], v[196:199], v[38:41]
	v_mfma_i32_16x16x64_i8 v[34:37], v[174:177], v[196:199], v[34:37]
	v_mfma_i32_16x16x64_i8 v[22:25], v[146:149], v[204:207], v[22:25]
	v_mfma_i32_16x16x64_i8 v[18:21], v[174:177], v[204:207], v[18:21]
	v_mfma_i32_16x16x64_i8 v[6:9], v[146:149], v[212:215], v[6:9]
	v_mfma_i32_16x16x64_i8 v[2:5], v[174:177], v[212:215], v[2:5]
	v_mfma_i32_16x16x64_i8 v[54:57], v[150:153], v[192:195], v[54:57]
	v_mfma_i32_16x16x64_i8 v[50:53], v[184:187], v[192:195], v[50:53]
	v_mfma_i32_16x16x64_i8 v[38:41], v[150:153], v[200:203], v[38:41]
	v_mfma_i32_16x16x64_i8 v[34:37], v[184:187], v[200:203], v[34:37]
	v_mfma_i32_16x16x64_i8 v[22:25], v[150:153], v[208:211], v[22:25]
	v_mfma_i32_16x16x64_i8 v[18:21], v[184:187], v[208:211], v[18:21]
	v_mfma_i32_16x16x64_i8 v[6:9], v[150:153], v[216:219], v[6:9]
	v_mfma_i32_16x16x64_i8 v[2:5], v[184:187], v[216:219], v[2:5]
	s_add_i32 s49, s49, 2
	s_add_u32 s18, s18, 0x10000
	s_addc_u32 s19, s19, 0
	s_add_u32 s47, s47, 0x10000
	s_addc_u32 s48, s48, 0
	s_cmpk_gt_u32 s49, 0x53
	s_barrier
	s_cbranch_scc0 .LBB0_1393
	s_and_b64 vcc, exec, s[14:15]
	s_cbranch_vccz .LBB0_1396
	s_barrier

; #define PG8_STAGE(bufoff, gbase, voff) do { _Pragma("unroll") for (int _i = 0; _i < 2; ++_i) \
;         __builtin_amdgcn_global_load_lds((const unsigned*)((const char*)(gbase) + (voff)[_i]), (LAS unsigned*)(lds + (bufoff) + ldsw + _i * 8192), 16, 0, 0); } while (0)
; #define PG8_LDA(dst, b, h) do { _Pragma("unroll") for (int m = 0; m < 4; ++m) _Pragma("unroll") for (int k = 0; k < 2; ++k) dst[m][k] = *(const LAS bf16x8*)(lds + PG8_SA(b, h) + aoff + m * 2048 + k * 1024); } while (0)
; #define PG8_LDB(dst, b, h) do { _Pragma("unroll") for (int n = 0; n < 2; ++n) _Pragma("unroll") for (int k = 0; k < 2; ++k) dst[n][k] = *(const LAS bf16x8*)(lds + PG8_SB(b, h) + boff + n * 2048 + k * 1024); } while (0)
; #define PG8_WAIT_V(n) asm volatile("s_waitcnt vmcnt(" #n ")" ::: "memory")
; #define PG8_WAIT_L(n) asm volatile("s_waitcnt lgkmcnt(" #n ")" ::: "memory")
; #define PG8_BAR __builtin_amdgcn_s_barrier()
; #define PG8_SCHED __builtin_amdgcn_sched_barrier(0)
; template <class Epi, class Sched, bool I8 = false>
; __device__ __forceinline__ void gemm_phase(LAS unsigned char* lds, const Gemm g, const Sched& S, const Epi& E) {
;     ...
;             PG8_LDB(B0, 0, 0); PG8_LDB(B1, 0, 1); PG8_SCHED; PG8_LDA(At, 0, 0); PG8_STAGE(PG8_SA(1, 1), a1 + hstepA, voffA);
;             PG8_WAIT_V(8); PG8_WAIT_L(0); PG8_BAR; PG8_MMA(0, 0, At, B0); PG8_MMA(0, 1, At, B1); PG8_BAR; PG8_SCHED;
;             PG8_LDA(At, 0, 1); PG8_STAGE(PG8_SB(0, 0), b2, voffB); PG8_STAGE(PG8_SB(0, 1), b2 + hstepB, voffB); PG8_STAGE(PG8_SA(0, 0), a2, voffA);
;             PG8_WAIT_V(8); PG8_WAIT_L(0); PG8_BAR; PG8_MMA(1, 0, At, B0); PG8_MMA(1, 1, At, B1); PG8_BAR; PG8_SCHED;
.LBB0_1482:
	ds_read_b128 v[152:155], v182
	ds_read_b128 v[156:159], v182 offset:1024
	ds_read_b128 v[160:163], v182 offset:2048
	ds_read_b128 v[164:167], v182 offset:3072
	ds_read_b128 v[168:171], v183
	ds_read_b128 v[172:175], v183 offset:1024
	ds_read_b128 v[176:179], v183 offset:2048
	ds_read_b128 v[186:189], v183 offset:3072
	s_add_u32 s38, s8, 0x4000
	s_addc_u32 s39, s9, 0
	s_cmp_eq_u32 s47, 60
	s_cselect_b32 s42, s31, s38
	s_cselect_b32 s43, s7, s39
	s_cselect_b32 s40, s44, s45
	s_cselect_b32 s41, s29, s46
	s_add_u32 s38, s42, 0x8000
	s_addc_u32 s39, s43, 0
	s_sub_u32 s98, s8, 0x4000
	s_subb_u32 s99, s9, 0
	s_mov_b32 m0, s58
	s_nop 0
	global_load_lds_dwordx4 v130, s[98:99]
	s_mov_b32 m0, s59
	s_nop 0
	global_load_lds_dwordx4 v134, s[98:99]
	s_add_i32 m0, s33, 0xc000
	ds_read_b128 v[190:193], v184
	ds_read_b128 v[194:197], v184 offset:1024
	ds_read_b128 v[198:201], v184 offset:2048
	ds_read_b128 v[202:205], v184 offset:3072
	ds_read_b128 v[206:209], v184 offset:4096
	ds_read_b128 v[210:213], v184 offset:5120
	ds_read_b128 v[214:217], v184 offset:6144
	ds_read_b128 v[218:221], v184 offset:7168
	global_load_lds_dwordx4 v144, s[8:9]
	s_add_i32 m0, s33, 0xe000
	s_nop 0
	global_load_lds_dwordx4 v146, s[8:9]
	s_waitcnt vmcnt(8)
	s_waitcnt lgkmcnt(0)
	s_barrier
	s_waitcnt lgkmcnt(0)
	v_mfma_f32_16x16x32_bf16 v[126:129], v[152:155], v[190:193], v[126:129]
	v_mfma_f32_16x16x32_bf16 v[122:125], v[160:163], v[190:193], v[122:125]
	v_mfma_f32_16x16x32_bf16 v[110:113], v[152:155], v[198:201], v[110:113]
	v_mfma_f32_16x16x32_bf16 v[106:109], v[160:163], v[198:201], v[106:109]
	v_mfma_f32_16x16x32_bf16 v[94:97], v[152:155], v[206:209], v[94:97]
	v_mfma_f32_16x16x32_bf16 v[90:93], v[160:163], v[206:209], v[90:93]
	v_mfma_f32_16x16x32_bf16 v[78:81], v[152:155], v[214:217], v[78:81]
	v_mfma_f32_16x16x32_bf16 v[74:77], v[160:163], v[214:217], v[74:77]
	v_mfma_f32_16x16x32_bf16 v[126:129], v[156:159], v[194:197], v[126:129]
	v_mfma_f32_16x16x32_bf16 v[122:125], v[164:167], v[194:197], v[122:125]
	v_mfma_f32_16x16x32_bf16 v[110:113], v[156:159], v[202:205], v[110:113]
	v_mfma_f32_16x16x32_bf16 v[106:109], v[164:167], v[202:205], v[106:109]
	v_mfma_f32_16x16x32_bf16 v[94:97], v[156:159], v[210:213], v[94:97]
	v_mfma_f32_16x16x32_bf16 v[90:93], v[164:167], v[210:213], v[90:93]
	v_mfma_f32_16x16x32_bf16 v[78:81], v[156:159], v[218:221], v[78:81]
	v_mfma_f32_16x16x32_bf16 v[74:77], v[164:167], v[218:221], v[74:77]
	v_mfma_f32_16x16x32_bf16 v[118:121], v[168:171], v[190:193], v[118:121]
	v_mfma_f32_16x16x32_bf16 v[114:117], v[176:179], v[190:193], v[114:117]
	v_mfma_f32_16x16x32_bf16 v[102:105], v[168:171], v[198:201], v[102:105]
	v_mfma_f32_16x16x32_bf16 v[98:101], v[176:179], v[198:201], v[98:101]
	v_mfma_f32_16x16x32_bf16 v[86:89], v[168:171], v[206:209], v[86:89]
	v_mfma_f32_16x16x32_bf16 v[82:85], v[176:179], v[206:209], v[82:85]
	v_mfma_f32_16x16x32_bf16 v[70:73], v[168:171], v[214:217], v[70:73]
	v_mfma_f32_16x16x32_bf16 v[66:69], v[176:179], v[214:217], v[66:69]
	v_mfma_f32_16x16x32_bf16 v[118:121], v[172:175], v[194:197], v[118:121]
	v_mfma_f32_16x16x32_bf16 v[114:117], v[186:189], v[194:197], v[114:117]
	v_mfma_f32_16x16x32_bf16 v[102:105], v[172:175], v[202:205], v[102:105]
	v_mfma_f32_16x16x32_bf16 v[98:101], v[186:189], v[202:205], v[98:101]
	v_mfma_f32_16x16x32_bf16 v[86:89], v[172:175], v[210:213], v[86:89]
	v_mfma_f32_16x16x32_bf16 v[82:85], v[186:189], v[210:213], v[82:85]
	v_mfma_f32_16x16x32_bf16 v[70:73], v[172:175], v[218:221], v[70:73]
	v_mfma_f32_16x16x32_bf16 v[66:69], v[186:189], v[218:221], v[66:69]
	s_barrier
	s_add_i32 s48, s63, s25
	s_mov_b32 m0, s48
	ds_read_b128 v[190:193], v184 offset:16384
	ds_read_b128 v[194:197], v184 offset:17408
	ds_read_b128 v[198:201], v184 offset:18432
	ds_read_b128 v[202:205], v184 offset:19456
	ds_read_b128 v[206:209], v184 offset:20480
	ds_read_b128 v[210:213], v184 offset:21504
	ds_read_b128 v[214:217], v184 offset:22528
	ds_read_b128 v[218:221], v184 offset:23552
	global_load_lds_dwordx4 v132, s[40:41]
	s_add_i32 m0, s48, 0x2000
	s_add_u32 s48, s40, 0x4000
	s_addc_u32 s49, s41, 0
	s_add_i32 s50, s64, s25
	global_load_lds_dwordx4 v136, s[40:41]
	s_mov_b32 m0, s50
	s_nop 0
	global_load_lds_dwordx4 v132, s[48:49]
	s_add_i32 m0, s50, 0x2000
	s_nop 0
	global_load_lds_dwordx4 v136, s[48:49]
	s_waitcnt vmcnt(6)
	s_waitcnt lgkmcnt(0)
	s_barrier
	s_waitcnt lgkmcnt(0)
	v_mfma_f32_16x16x32_bf16 v[62:65], v[152:155], v[190:193], v[62:65]
	v_mfma_f32_16x16x32_bf16 v[58:61], v[160:163], v[190:193], v[58:61]
	v_mfma_f32_16x16x32_bf16 v[46:49], v[152:155], v[198:201], v[46:49]
	v_mfma_f32_16x16x32_bf16 v[42:45], v[160:163], v[198:201], v[42:45]
	v_mfma_f32_16x16x32_bf16 v[30:33], v[152:155], v[206:209], v[30:33]
	v_mfma_f32_16x16x32_bf16 v[26:29], v[160:163], v[206:209], v[26:29]
	v_mfma_f32_16x16x32_bf16 v[14:17], v[152:155], v[214:217], v[14:17]
	v_mfma_f32_16x16x32_bf16 v[10:13], v[160:163], v[214:217], v[10:13]
	v_mfma_f32_16x16x32_bf16 v[62:65], v[156:159], v[194:197], v[62:65]
	v_mfma_f32_16x16x32_bf16 v[58:61], v[164:167], v[194:197], v[58:61]
	v_mfma_f32_16x16x32_bf16 v[46:49], v[156:159], v[202:205], v[46:49]
	v_mfma_f32_16x16x32_bf16 v[42:45], v[164:167], v[202:205], v[42:45]
	v_mfma_f32_16x16x32_bf16 v[30:33], v[156:159], v[210:213], v[30:33]
	v_mfma_f32_16x16x32_bf16 v[26:29], v[164:167], v[210:213], v[26:29]
	v_mfma_f32_16x16x32_bf16 v[14:17], v[156:159], v[218:221], v[14:17]
	v_mfma_f32_16x16x32_bf16 v[10:13], v[164:167], v[218:221], v[10:13]
	v_mfma_f32_16x16x32_bf16 v[54:57], v[168:171], v[190:193], v[54:57]
	v_mfma_f32_16x16x32_bf16 v[50:53], v[176:179], v[190:193], v[50:53]
	v_mfma_f32_16x16x32_bf16 v[38:41], v[168:171], v[198:201], v[38:41]
	v_mfma_f32_16x16x32_bf16 v[34:37], v[176:179], v[198:201], v[34:37]
	v_mfma_f32_16x16x32_bf16 v[22:25], v[168:171], v[206:209], v[22:25]
	v_mfma_f32_16x16x32_bf16 v[18:21], v[176:179], v[206:209], v[18:21]
	v_mfma_f32_16x16x32_bf16 v[6:9], v[168:171], v[214:217], v[6:9]
	v_mfma_f32_16x16x32_bf16 v[2:5], v[176:179], v[214:217], v[2:5]
	v_mfma_f32_16x16x32_bf16 v[54:57], v[172:175], v[194:197], v[54:57]
	v_mfma_f32_16x16x32_bf16 v[50:53], v[186:189], v[194:197], v[50:53]
	v_mfma_f32_16x16x32_bf16 v[38:41], v[172:175], v[202:205], v[38:41]
	v_mfma_f32_16x16x32_bf16 v[34:37], v[186:189], v[202:205], v[34:37]
	v_mfma_f32_16x16x32_bf16 v[22:25], v[172:175], v[210:213], v[22:25]
	v_mfma_f32_16x16x32_bf16 v[18:21], v[186:189], v[210:213], v[18:21]
	v_mfma_f32_16x16x32_bf16 v[6:9], v[172:175], v[218:221], v[6:9]
	v_mfma_f32_16x16x32_bf16 v[2:5], v[186:189], v[218:221], v[2:5]
	s_barrier
; #define PG8_STAGE(bufoff, gbase, voff) do { _Pragma("unroll") for (int _i = 0; _i < 2; ++_i) \
;         __builtin_amdgcn_global_load_lds((const unsigned*)((const char*)(gbase) + (voff)[_i]), (LAS unsigned*)(lds + (bufoff) + ldsw + _i * 8192), 16, 0, 0); } while (0)
; #define PG8_LDA(dst, b, h) do { _Pragma("unroll") for (int m = 0; m < 4; ++m) _Pragma("unroll") for (int k = 0; k < 2; ++k) dst[m][k] = *(const LAS bf16x8*)(lds + PG8_SA(b, h) + aoff + m * 2048 + k * 1024); } while (0)
; #define PG8_LDB(dst, b, h) do { _Pragma("unroll") for (int n = 0; n < 2; ++n) _Pragma("unroll") for (int k = 0; k < 2; ++k) dst[n][k] = *(const LAS bf16x8*)(lds + PG8_SB(b, h) + boff + n * 2048 + k * 1024); } while (0)
; #define PG8_WAIT_V(n) asm volatile("s_waitcnt vmcnt(" #n ")" ::: "memory")
; #define PG8_WAIT_L(n) asm volatile("s_waitcnt lgkmcnt(" #n ")" ::: "memory")
; #define PG8_BAR __builtin_amdgcn_s_barrier()
; #define PG8_SCHED __builtin_amdgcn_sched_barrier(0)
; template <class Epi, class Sched, bool I8 = false>
; __device__ __forceinline__ void gemm_phase(LAS unsigned char* lds, const Gemm g, const Sched& S, const Epi& E) {
;     ...
;             PG8_LDB(B0, 1, 0); PG8_LDB(B1, 1, 1); PG8_SCHED; PG8_LDA(At, 1, 0); PG8_STAGE(PG8_SA(0, 1), a2 + hstepA, voffA);
;             PG8_WAIT_V(8); PG8_WAIT_L(0); PG8_BAR; PG8_MMA(0, 0, At, B0); PG8_MMA(0, 1, At, B1); PG8_BAR; PG8_SCHED;
;             PG8_LDA(At, 1, 1); PG8_STAGE(PG8_SB(1, 0), b3, voffB); PG8_STAGE(PG8_SB(1, 1), b3 + hstepB, voffB); PG8_STAGE(PG8_SA(1, 0), a3, voffA);
;             PG8_WAIT_V(8); PG8_WAIT_L(0); PG8_BAR; PG8_MMA(1, 0, At, B0); PG8_MMA(1, 1, At, B1); PG8_BAR; PG8_SCHED;
	s_add_i32 s48, 0, 0x18000
	v_add_u32_e32 v138, s48, v181
	s_add_i32 s49, 0, 0x1c000
	ds_read_b128 v[152:155], v138
	ds_read_b128 v[156:159], v138 offset:1024
	ds_read_b128 v[160:163], v138 offset:2048
	ds_read_b128 v[164:167], v138 offset:3072
	v_add_u32_e32 v138, s49, v181
	ds_read_b128 v[168:171], v138
	ds_read_b128 v[172:175], v138 offset:1024
	ds_read_b128 v[176:179], v138 offset:2048
	ds_read_b128 v[186:189], v138 offset:3072
	s_mov_b32 m0, s33
	s_nop 0
	global_load_lds_dwordx4 v130, s[42:43]
	s_mov_b32 m0, s52
	s_nop 0
	global_load_lds_dwordx4 v134, s[42:43]
	s_add_u32 s42, s42, 0x4000
	s_addc_u32 s43, s43, 0
	s_mov_b32 m0, s53
	ds_read_b128 v[190:193], v184 offset:32768
	ds_read_b128 v[194:197], v184 offset:33792
	ds_read_b128 v[198:201], v184 offset:34816
	ds_read_b128 v[202:205], v184 offset:35840
	ds_read_b128 v[206:209], v184 offset:36864
	ds_read_b128 v[210:213], v184 offset:37888
	ds_read_b128 v[214:217], v184 offset:38912
	ds_read_b128 v[218:221], v184 offset:39936
	global_load_lds_dwordx4 v130, s[42:43]
	s_mov_b32 m0, s54
	s_nop 0
	global_load_lds_dwordx4 v134, s[42:43]
	s_waitcnt vmcnt(8)
	s_waitcnt lgkmcnt(0)
	s_barrier
	s_waitcnt lgkmcnt(0)
	v_mfma_f32_16x16x32_bf16 v[126:129], v[152:155], v[190:193], v[126:129]
	v_mfma_f32_16x16x32_bf16 v[122:125], v[160:163], v[190:193], v[122:125]
	v_mfma_f32_16x16x32_bf16 v[110:113], v[152:155], v[198:201], v[110:113]
	v_mfma_f32_16x16x32_bf16 v[106:109], v[160:163], v[198:201], v[106:109]
	v_mfma_f32_16x16x32_bf16 v[94:97], v[152:155], v[206:209], v[94:97]
	v_mfma_f32_16x16x32_bf16 v[90:93], v[160:163], v[206:209], v[90:93]
	v_mfma_f32_16x16x32_bf16 v[78:81], v[152:155], v[214:217], v[78:81]
	v_mfma_f32_16x16x32_bf16 v[74:77], v[160:163], v[214:217], v[74:77]
	v_mfma_f32_16x16x32_bf16 v[126:129], v[156:159], v[194:197], v[126:129]
	v_mfma_f32_16x16x32_bf16 v[122:125], v[164:167], v[194:197], v[122:125]
	v_mfma_f32_16x16x32_bf16 v[110:113], v[156:159], v[202:205], v[110:113]
	v_mfma_f32_16x16x32_bf16 v[106:109], v[164:167], v[202:205], v[106:109]
	v_mfma_f32_16x16x32_bf16 v[94:97], v[156:159], v[210:213], v[94:97]
	v_mfma_f32_16x16x32_bf16 v[90:93], v[164:167], v[210:213], v[90:93]
	v_mfma_f32_16x16x32_bf16 v[78:81], v[156:159], v[218:221], v[78:81]
	v_mfma_f32_16x16x32_bf16 v[74:77], v[164:167], v[218:221], v[74:77]
	v_mfma_f32_16x16x32_bf16 v[118:121], v[168:171], v[190:193], v[118:121]
	v_mfma_f32_16x16x32_bf16 v[114:117], v[176:179], v[190:193], v[114:117]
	v_mfma_f32_16x16x32_bf16 v[102:105], v[168:171], v[198:201], v[102:105]
	v_mfma_f32_16x16x32_bf16 v[98:101], v[176:179], v[198:201], v[98:101]
	v_mfma_f32_16x16x32_bf16 v[86:89], v[168:171], v[206:209], v[86:89]
	v_mfma_f32_16x16x32_bf16 v[82:85], v[176:179], v[206:209], v[82:85]
	v_mfma_f32_16x16x32_bf16 v[70:73], v[168:171], v[214:217], v[70:73]
	v_mfma_f32_16x16x32_bf16 v[66:69], v[176:179], v[214:217], v[66:69]
	v_mfma_f32_16x16x32_bf16 v[118:121], v[172:175], v[194:197], v[118:121]
	v_mfma_f32_16x16x32_bf16 v[114:117], v[186:189], v[194:197], v[114:117]
	v_mfma_f32_16x16x32_bf16 v[102:105], v[172:175], v[202:205], v[102:105]
	v_mfma_f32_16x16x32_bf16 v[98:101], v[186:189], v[202:205], v[98:101]
	v_mfma_f32_16x16x32_bf16 v[86:89], v[172:175], v[210:213], v[86:89]
	v_mfma_f32_16x16x32_bf16 v[82:85], v[186:189], v[210:213], v[82:85]
	v_mfma_f32_16x16x32_bf16 v[70:73], v[172:175], v[218:221], v[70:73]
	v_mfma_f32_16x16x32_bf16 v[66:69], v[186:189], v[218:221], v[66:69]
	s_barrier
	s_add_u32 s42, s40, 0x8000
	s_addc_u32 s43, s41, 0
	s_add_i32 s48, s48, s25
	s_mov_b32 m0, s48
	ds_read_b128 v[190:193], v184 offset:49152
	ds_read_b128 v[194:197], v184 offset:50176
	ds_read_b128 v[198:201], v184 offset:51200
	ds_read_b128 v[202:205], v184 offset:52224
	ds_read_b128 v[206:209], v184 offset:53248
	ds_read_b128 v[210:213], v184 offset:54272
	ds_read_b128 v[214:217], v184 offset:55296
	ds_read_b128 v[218:221], v184 offset:56320
	global_load_lds_dwordx4 v132, s[42:43]
	s_add_i32 m0, s48, 0x2000
	s_add_u32 s40, s40, 0xc000
	v_lshl_add_u64 v[222:223], s[42:43], 0, v[136:137]
	s_addc_u32 s41, s41, 0
	s_add_i32 s42, s49, s25
	global_load_lds_dwordx4 v[222:223], off
	s_mov_b32 m0, s42
	s_nop 0
	global_load_lds_dwordx4 v132, s[40:41]
	s_add_i32 m0, s42, 0x2000
	s_nop 0
	global_load_lds_dwordx4 v136, s[40:41]
	s_waitcnt vmcnt(6)
	s_waitcnt lgkmcnt(0)
	s_barrier
	s_waitcnt lgkmcnt(0)
	v_mfma_f32_16x16x32_bf16 v[62:65], v[152:155], v[190:193], v[62:65]
	v_mfma_f32_16x16x32_bf16 v[58:61], v[160:163], v[190:193], v[58:61]
	v_mfma_f32_16x16x32_bf16 v[46:49], v[152:155], v[198:201], v[46:49]
	v_mfma_f32_16x16x32_bf16 v[42:45], v[160:163], v[198:201], v[42:45]
	v_mfma_f32_16x16x32_bf16 v[30:33], v[152:155], v[206:209], v[30:33]
	v_mfma_f32_16x16x32_bf16 v[26:29], v[160:163], v[206:209], v[26:29]
	v_mfma_f32_16x16x32_bf16 v[14:17], v[152:155], v[214:217], v[14:17]
	v_mfma_f32_16x16x32_bf16 v[10:13], v[160:163], v[214:217], v[10:13]
	v_mfma_f32_16x16x32_bf16 v[62:65], v[156:159], v[194:197], v[62:65]
	v_mfma_f32_16x16x32_bf16 v[58:61], v[164:167], v[194:197], v[58:61]
	v_mfma_f32_16x16x32_bf16 v[46:49], v[156:159], v[202:205], v[46:49]
	v_mfma_f32_16x16x32_bf16 v[42:45], v[164:167], v[202:205], v[42:45]
	v_mfma_f32_16x16x32_bf16 v[30:33], v[156:159], v[210:213], v[30:33]
	v_mfma_f32_16x16x32_bf16 v[26:29], v[164:167], v[210:213], v[26:29]
	v_mfma_f32_16x16x32_bf16 v[14:17], v[156:159], v[218:221], v[14:17]
	v_mfma_f32_16x16x32_bf16 v[10:13], v[164:167], v[218:221], v[10:13]
	v_mfma_f32_16x16x32_bf16 v[54:57], v[168:171], v[190:193], v[54:57]
	v_mfma_f32_16x16x32_bf16 v[50:53], v[176:179], v[190:193], v[50:53]
	v_mfma_f32_16x16x32_bf16 v[38:41], v[168:171], v[198:201], v[38:41]
	v_mfma_f32_16x16x32_bf16 v[34:37], v[176:179], v[198:201], v[34:37]
	v_mfma_f32_16x16x32_bf16 v[22:25], v[168:171], v[206:209], v[22:25]
	v_mfma_f32_16x16x32_bf16 v[18:21], v[176:179], v[206:209], v[18:21]
	v_mfma_f32_16x16x32_bf16 v[6:9], v[168:171], v[214:217], v[6:9]
	v_mfma_f32_16x16x32_bf16 v[2:5], v[176:179], v[214:217], v[2:5]
	v_mfma_f32_16x16x32_bf16 v[54:57], v[172:175], v[194:197], v[54:57]
	v_mfma_f32_16x16x32_bf16 v[50:53], v[186:189], v[194:197], v[50:53]
	v_mfma_f32_16x16x32_bf16 v[38:41], v[172:175], v[202:205], v[38:41]
	v_mfma_f32_16x16x32_bf16 v[34:37], v[186:189], v[202:205], v[34:37]
	v_mfma_f32_16x16x32_bf16 v[22:25], v[172:175], v[210:213], v[22:25]
	v_mfma_f32_16x16x32_bf16 v[18:21], v[186:189], v[210:213], v[18:21]
	v_mfma_f32_16x16x32_bf16 v[6:9], v[172:175], v[218:221], v[6:9]
	v_mfma_f32_16x16x32_bf16 v[2:5], v[186:189], v[218:221], v[2:5]
	s_add_i32 s47, s47, 2
	s_add_u32 s8, s8, 0x10000
	s_addc_u32 s9, s9, 0
	s_add_u32 s45, s45, 0x10000
	s_addc_u32 s46, s46, 0
	s_cmp_gt_u32 s47, 61
	s_barrier
	s_cbranch_scc0 .LBB0_1482
	s_and_b64 vcc, exec, s[20:21]
	s_cbranch_vccz .LBB0_1485
	s_barrier

; #define PG8_STAGE(bufoff, gbase, voff) do { _Pragma("unroll") for (int _i = 0; _i < 2; ++_i) \
;         __builtin_amdgcn_global_load_lds((const unsigned*)((const char*)(gbase) + (voff)[_i]), (LAS unsigned*)(lds + (bufoff) + ldsw + _i * 8192), 16, 0, 0); } while (0)
; #define PG8_LDA(dst, b, h) do { _Pragma("unroll") for (int m = 0; m < 4; ++m) _Pragma("unroll") for (int k = 0; k < 2; ++k) dst[m][k] = *(const LAS bf16x8*)(lds + PG8_SA(b, h) + aoff + m * 2048 + k * 1024); } while (0)
; #define PG8_LDB(dst, b, h) do { _Pragma("unroll") for (int n = 0; n < 2; ++n) _Pragma("unroll") for (int k = 0; k < 2; ++k) dst[n][k] = *(const LAS bf16x8*)(lds + PG8_SB(b, h) + boff + n * 2048 + k * 1024); } while (0)
; #define PG8_WAIT_V(n) asm volatile("s_waitcnt vmcnt(" #n ")" ::: "memory")
; #define PG8_WAIT_L(n) asm volatile("s_waitcnt lgkmcnt(" #n ")" ::: "memory")
; #define PG8_BAR __builtin_amdgcn_s_barrier()
; #define PG8_SCHED __builtin_amdgcn_sched_barrier(0)
; template <class Epi, class Sched, bool I8 = false>
; __device__ __forceinline__ void gemm_phase(LAS unsigned char* lds, const Gemm g, const Sched& S, const Epi& E) {
;     ...
;             PG8_LDB(B0, 0, 0); PG8_LDB(B1, 0, 1); PG8_SCHED; PG8_LDA(At, 0, 0); PG8_STAGE(PG8_SA(1, 1), a1 + hstepA, voffA);
;             PG8_WAIT_V(8); PG8_WAIT_L(0); PG8_BAR; PG8_MMA(0, 0, At, B0); PG8_MMA(0, 1, At, B1); PG8_BAR; PG8_SCHED;
;             PG8_LDA(At, 0, 1); PG8_STAGE(PG8_SB(0, 0), b2, voffB); PG8_STAGE(PG8_SB(0, 1), b2 + hstepB, voffB); PG8_STAGE(PG8_SA(0, 0), a2, voffA);
;             PG8_WAIT_V(8); PG8_WAIT_L(0); PG8_BAR; PG8_MMA(1, 0, At, B0); PG8_MMA(1, 1, At, B1); PG8_BAR; PG8_SCHED;
.LBB0_2685:
	ds_read_b128 v[130:133], v166
	ds_read_b128 v[134:137], v166 offset:1024
	ds_read_b128 v[158:161], v166 offset:2048
	ds_read_b128 v[170:173], v166 offset:3072
	ds_read_b128 v[174:177], v167
	ds_read_b128 v[178:181], v167 offset:1024
	ds_read_b128 v[182:185], v167 offset:2048
	ds_read_b128 v[186:189], v167 offset:3072
	s_add_u32 s12, s10, 0x4000
	s_addc_u32 s13, s11, 0
	s_cmp_eq_u32 s45, 4
	s_cselect_b32 s16, s40, s12
	s_cselect_b32 s17, s39, s13
	s_cselect_b32 s14, s42, s43
	s_cselect_b32 s15, s41, s44
	s_add_u32 s12, s16, 0x8000
	s_addc_u32 s13, s17, 0
	s_sub_u32 s98, s10, 0x4000
	s_subb_u32 s99, s11, 0
	s_mov_b32 m0, s33
	s_nop 0
	global_load_lds_dwordx4 v144, s[98:99]
	s_mov_b32 m0, s34
	s_nop 0
	global_load_lds_dwordx4 v140, s[98:99]
	s_add_i32 m0, s26, 0xc000
	ds_read_b128 v[190:193], v168
	ds_read_b128 v[194:197], v168 offset:1024
	ds_read_b128 v[198:201], v168 offset:2048
	ds_read_b128 v[202:205], v168 offset:3072
	ds_read_b128 v[206:209], v168 offset:4096
	ds_read_b128 v[210:213], v168 offset:5120
	ds_read_b128 v[214:217], v168 offset:6144
	ds_read_b128 v[218:221], v168 offset:7168
	global_load_lds_dwordx4 v150, s[10:11]
	s_add_i32 m0, s26, 0xe000
	s_nop 0
	global_load_lds_dwordx4 v152, s[10:11]
	s_waitcnt vmcnt(8)
	s_waitcnt lgkmcnt(0)
	s_barrier
	s_waitcnt lgkmcnt(0)
	v_mfma_f32_16x16x32_bf16 v[126:129], v[130:133], v[190:193], v[126:129]
	v_mfma_f32_16x16x32_bf16 v[122:125], v[158:161], v[190:193], v[122:125]
	v_mfma_f32_16x16x32_bf16 v[118:121], v[130:133], v[198:201], v[118:121]
	v_mfma_f32_16x16x32_bf16 v[114:117], v[158:161], v[198:201], v[114:117]
	v_mfma_f32_16x16x32_bf16 v[110:113], v[130:133], v[206:209], v[110:113]
	v_mfma_f32_16x16x32_bf16 v[106:109], v[158:161], v[206:209], v[106:109]
	v_mfma_f32_16x16x32_bf16 v[102:105], v[130:133], v[214:217], v[102:105]
	v_mfma_f32_16x16x32_bf16 v[98:101], v[158:161], v[214:217], v[98:101]
	v_mfma_f32_16x16x32_bf16 v[126:129], v[134:137], v[194:197], v[126:129]
	v_mfma_f32_16x16x32_bf16 v[122:125], v[170:173], v[194:197], v[122:125]
	v_mfma_f32_16x16x32_bf16 v[118:121], v[134:137], v[202:205], v[118:121]
	v_mfma_f32_16x16x32_bf16 v[114:117], v[170:173], v[202:205], v[114:117]
	v_mfma_f32_16x16x32_bf16 v[110:113], v[134:137], v[210:213], v[110:113]
	v_mfma_f32_16x16x32_bf16 v[106:109], v[170:173], v[210:213], v[106:109]
	v_mfma_f32_16x16x32_bf16 v[102:105], v[134:137], v[218:221], v[102:105]
	v_mfma_f32_16x16x32_bf16 v[98:101], v[170:173], v[218:221], v[98:101]
	v_mfma_f32_16x16x32_bf16 v[62:65], v[174:177], v[190:193], v[62:65]
	v_mfma_f32_16x16x32_bf16 v[58:61], v[182:185], v[190:193], v[58:61]
	v_mfma_f32_16x16x32_bf16 v[54:57], v[174:177], v[198:201], v[54:57]
	v_mfma_f32_16x16x32_bf16 v[50:53], v[182:185], v[198:201], v[50:53]
	v_mfma_f32_16x16x32_bf16 v[46:49], v[174:177], v[206:209], v[46:49]
	v_mfma_f32_16x16x32_bf16 v[42:45], v[182:185], v[206:209], v[42:45]
	v_mfma_f32_16x16x32_bf16 v[38:41], v[174:177], v[214:217], v[38:41]
	v_mfma_f32_16x16x32_bf16 v[34:37], v[182:185], v[214:217], v[34:37]
	v_mfma_f32_16x16x32_bf16 v[62:65], v[178:181], v[194:197], v[62:65]
	v_mfma_f32_16x16x32_bf16 v[58:61], v[186:189], v[194:197], v[58:61]
	v_mfma_f32_16x16x32_bf16 v[54:57], v[178:181], v[202:205], v[54:57]
	v_mfma_f32_16x16x32_bf16 v[50:53], v[186:189], v[202:205], v[50:53]
	v_mfma_f32_16x16x32_bf16 v[46:49], v[178:181], v[210:213], v[46:49]
	v_mfma_f32_16x16x32_bf16 v[42:45], v[186:189], v[210:213], v[42:45]
	v_mfma_f32_16x16x32_bf16 v[38:41], v[178:181], v[218:221], v[38:41]
	v_mfma_f32_16x16x32_bf16 v[34:37], v[186:189], v[218:221], v[34:37]
	s_barrier
	s_add_i32 s46, s62, s22
	s_mov_b32 m0, s46
	ds_read_b128 v[190:193], v168 offset:16384
	ds_read_b128 v[194:197], v168 offset:17408
	ds_read_b128 v[198:201], v168 offset:18432
	ds_read_b128 v[202:205], v168 offset:19456
	ds_read_b128 v[206:209], v168 offset:20480
	ds_read_b128 v[210:213], v168 offset:21504
	ds_read_b128 v[214:217], v168 offset:22528
	ds_read_b128 v[218:221], v168 offset:23552
	global_load_lds_dwordx4 v142, s[14:15]
	s_add_i32 m0, s46, 0x2000
	s_add_u32 s46, s14, 0x4000
	s_addc_u32 s47, s15, 0
	s_add_i32 s48, s35, s22
	global_load_lds_dwordx4 v138, s[14:15]
	s_mov_b32 m0, s48
	s_nop 0
	global_load_lds_dwordx4 v142, s[46:47]
	s_add_i32 m0, s48, 0x2000
	s_nop 0
	global_load_lds_dwordx4 v138, s[46:47]
	s_waitcnt vmcnt(6)
	s_waitcnt lgkmcnt(0)
	s_barrier
	s_waitcnt lgkmcnt(0)
	v_mfma_f32_16x16x32_bf16 v[94:97], v[130:133], v[190:193], v[94:97]
	v_mfma_f32_16x16x32_bf16 v[90:93], v[158:161], v[190:193], v[90:93]
	v_mfma_f32_16x16x32_bf16 v[86:89], v[130:133], v[198:201], v[86:89]
	v_mfma_f32_16x16x32_bf16 v[82:85], v[158:161], v[198:201], v[82:85]
	v_mfma_f32_16x16x32_bf16 v[78:81], v[130:133], v[206:209], v[78:81]
	v_mfma_f32_16x16x32_bf16 v[74:77], v[158:161], v[206:209], v[74:77]
	v_mfma_f32_16x16x32_bf16 v[70:73], v[130:133], v[214:217], v[70:73]
	v_mfma_f32_16x16x32_bf16 v[66:69], v[158:161], v[214:217], v[66:69]
	v_mfma_f32_16x16x32_bf16 v[94:97], v[134:137], v[194:197], v[94:97]
	v_mfma_f32_16x16x32_bf16 v[90:93], v[170:173], v[194:197], v[90:93]
	v_mfma_f32_16x16x32_bf16 v[86:89], v[134:137], v[202:205], v[86:89]
	v_mfma_f32_16x16x32_bf16 v[82:85], v[170:173], v[202:205], v[82:85]
	v_mfma_f32_16x16x32_bf16 v[78:81], v[134:137], v[210:213], v[78:81]
	v_mfma_f32_16x16x32_bf16 v[74:77], v[170:173], v[210:213], v[74:77]
	v_mfma_f32_16x16x32_bf16 v[70:73], v[134:137], v[218:221], v[70:73]
	v_mfma_f32_16x16x32_bf16 v[66:69], v[170:173], v[218:221], v[66:69]
	v_mfma_f32_16x16x32_bf16 v[30:33], v[174:177], v[190:193], v[30:33]
	v_mfma_f32_16x16x32_bf16 v[26:29], v[182:185], v[190:193], v[26:29]
	v_mfma_f32_16x16x32_bf16 v[22:25], v[174:177], v[198:201], v[22:25]
	v_mfma_f32_16x16x32_bf16 v[18:21], v[182:185], v[198:201], v[18:21]
	v_mfma_f32_16x16x32_bf16 v[14:17], v[174:177], v[206:209], v[14:17]
	v_mfma_f32_16x16x32_bf16 v[10:13], v[182:185], v[206:209], v[10:13]
	v_mfma_f32_16x16x32_bf16 v[6:9], v[174:177], v[214:217], v[6:9]
	v_mfma_f32_16x16x32_bf16 v[2:5], v[182:185], v[214:217], v[2:5]
	v_mfma_f32_16x16x32_bf16 v[30:33], v[178:181], v[194:197], v[30:33]
	v_mfma_f32_16x16x32_bf16 v[26:29], v[186:189], v[194:197], v[26:29]
	v_mfma_f32_16x16x32_bf16 v[22:25], v[178:181], v[202:205], v[22:25]
	v_mfma_f32_16x16x32_bf16 v[18:21], v[186:189], v[202:205], v[18:21]
	v_mfma_f32_16x16x32_bf16 v[14:17], v[178:181], v[210:213], v[14:17]
	v_mfma_f32_16x16x32_bf16 v[10:13], v[186:189], v[210:213], v[10:13]
	v_mfma_f32_16x16x32_bf16 v[6:9], v[178:181], v[218:221], v[6:9]
	v_mfma_f32_16x16x32_bf16 v[2:5], v[186:189], v[218:221], v[2:5]
	s_barrier
; #define PG8_STAGE(bufoff, gbase, voff) do { _Pragma("unroll") for (int _i = 0; _i < 2; ++_i) \
;         __builtin_amdgcn_global_load_lds((const unsigned*)((const char*)(gbase) + (voff)[_i]), (LAS unsigned*)(lds + (bufoff) + ldsw + _i * 8192), 16, 0, 0); } while (0)
; #define PG8_LDA(dst, b, h) do { _Pragma("unroll") for (int m = 0; m < 4; ++m) _Pragma("unroll") for (int k = 0; k < 2; ++k) dst[m][k] = *(const LAS bf16x8*)(lds + PG8_SA(b, h) + aoff + m * 2048 + k * 1024); } while (0)
; #define PG8_LDB(dst, b, h) do { _Pragma("unroll") for (int n = 0; n < 2; ++n) _Pragma("unroll") for (int k = 0; k < 2; ++k) dst[n][k] = *(const LAS bf16x8*)(lds + PG8_SB(b, h) + boff + n * 2048 + k * 1024); } while (0)
; #define PG8_WAIT_V(n) asm volatile("s_waitcnt vmcnt(" #n ")" ::: "memory")
; #define PG8_WAIT_L(n) asm volatile("s_waitcnt lgkmcnt(" #n ")" ::: "memory")
; #define PG8_BAR __builtin_amdgcn_s_barrier()
; #define PG8_SCHED __builtin_amdgcn_sched_barrier(0)
; template <class Epi, class Sched, bool I8 = false>
; __device__ __forceinline__ void gemm_phase(LAS unsigned char* lds, const Gemm g, const Sched& S, const Epi& E) {
;     ...
;             PG8_LDB(B0, 1, 0); PG8_LDB(B1, 1, 1); PG8_SCHED; PG8_LDA(At, 1, 0); PG8_STAGE(PG8_SA(0, 1), a2 + hstepA, voffA);
;             PG8_WAIT_V(8); PG8_WAIT_L(0); PG8_BAR; PG8_MMA(0, 0, At, B0); PG8_MMA(0, 1, At, B1); PG8_BAR; PG8_SCHED;
;             PG8_LDA(At, 1, 1); PG8_STAGE(PG8_SB(1, 0), b3, voffB); PG8_STAGE(PG8_SB(1, 1), b3 + hstepB, voffB); PG8_STAGE(PG8_SA(1, 0), a3, voffA);
;             PG8_WAIT_V(8); PG8_WAIT_L(0); PG8_BAR; PG8_MMA(1, 0, At, B0); PG8_MMA(1, 1, At, B1); PG8_BAR; PG8_SCHED;
	s_add_i32 s46, 0, 0x18000
	v_add_u32_e32 v155, s46, v165
	s_add_i32 s47, 0, 0x1c000
	ds_read_b128 v[130:133], v155
	ds_read_b128 v[134:137], v155 offset:1024
	ds_read_b128 v[158:161], v155 offset:2048
	ds_read_b128 v[170:173], v155 offset:3072
	v_add_u32_e32 v155, s47, v165
	ds_read_b128 v[174:177], v155
	ds_read_b128 v[178:181], v155 offset:1024
	ds_read_b128 v[182:185], v155 offset:2048
	ds_read_b128 v[186:189], v155 offset:3072
	s_mov_b32 m0, s26
	s_nop 0
	global_load_lds_dwordx4 v144, s[16:17]
	s_mov_b32 m0, s27
	s_nop 0
	global_load_lds_dwordx4 v140, s[16:17]
	s_add_u32 s16, s16, 0x4000
	s_addc_u32 s17, s17, 0
	s_mov_b32 m0, s28
	ds_read_b128 v[190:193], v168 offset:32768
	ds_read_b128 v[194:197], v168 offset:33792
	ds_read_b128 v[198:201], v168 offset:34816
	ds_read_b128 v[202:205], v168 offset:35840
	ds_read_b128 v[206:209], v168 offset:36864
	ds_read_b128 v[210:213], v168 offset:37888
	ds_read_b128 v[214:217], v168 offset:38912
	ds_read_b128 v[218:221], v168 offset:39936
	global_load_lds_dwordx4 v144, s[16:17]
	s_mov_b32 m0, s29
	s_nop 0
	global_load_lds_dwordx4 v140, s[16:17]
	s_waitcnt vmcnt(8)
	s_waitcnt lgkmcnt(0)
	s_barrier
	s_waitcnt lgkmcnt(0)
	v_mfma_f32_16x16x32_bf16 v[126:129], v[130:133], v[190:193], v[126:129]
	v_mfma_f32_16x16x32_bf16 v[122:125], v[158:161], v[190:193], v[122:125]
	v_mfma_f32_16x16x32_bf16 v[118:121], v[130:133], v[198:201], v[118:121]
	v_mfma_f32_16x16x32_bf16 v[114:117], v[158:161], v[198:201], v[114:117]
	v_mfma_f32_16x16x32_bf16 v[110:113], v[130:133], v[206:209], v[110:113]
	v_mfma_f32_16x16x32_bf16 v[106:109], v[158:161], v[206:209], v[106:109]
	v_mfma_f32_16x16x32_bf16 v[102:105], v[130:133], v[214:217], v[102:105]
	v_mfma_f32_16x16x32_bf16 v[98:101], v[158:161], v[214:217], v[98:101]
	v_mfma_f32_16x16x32_bf16 v[126:129], v[134:137], v[194:197], v[126:129]
	v_mfma_f32_16x16x32_bf16 v[122:125], v[170:173], v[194:197], v[122:125]
	v_mfma_f32_16x16x32_bf16 v[118:121], v[134:137], v[202:205], v[118:121]
	v_mfma_f32_16x16x32_bf16 v[114:117], v[170:173], v[202:205], v[114:117]
	v_mfma_f32_16x16x32_bf16 v[110:113], v[134:137], v[210:213], v[110:113]
	v_mfma_f32_16x16x32_bf16 v[106:109], v[170:173], v[210:213], v[106:109]
	v_mfma_f32_16x16x32_bf16 v[102:105], v[134:137], v[218:221], v[102:105]
	v_mfma_f32_16x16x32_bf16 v[98:101], v[170:173], v[218:221], v[98:101]
	v_mfma_f32_16x16x32_bf16 v[62:65], v[174:177], v[190:193], v[62:65]
	v_mfma_f32_16x16x32_bf16 v[58:61], v[182:185], v[190:193], v[58:61]
	v_mfma_f32_16x16x32_bf16 v[54:57], v[174:177], v[198:201], v[54:57]
	v_mfma_f32_16x16x32_bf16 v[50:53], v[182:185], v[198:201], v[50:53]
	v_mfma_f32_16x16x32_bf16 v[46:49], v[174:177], v[206:209], v[46:49]
	v_mfma_f32_16x16x32_bf16 v[42:45], v[182:185], v[206:209], v[42:45]
	v_mfma_f32_16x16x32_bf16 v[38:41], v[174:177], v[214:217], v[38:41]
	v_mfma_f32_16x16x32_bf16 v[34:37], v[182:185], v[214:217], v[34:37]
	v_mfma_f32_16x16x32_bf16 v[62:65], v[178:181], v[194:197], v[62:65]
	v_mfma_f32_16x16x32_bf16 v[58:61], v[186:189], v[194:197], v[58:61]
	v_mfma_f32_16x16x32_bf16 v[54:57], v[178:181], v[202:205], v[54:57]
	v_mfma_f32_16x16x32_bf16 v[50:53], v[186:189], v[202:205], v[50:53]
	v_mfma_f32_16x16x32_bf16 v[46:49], v[178:181], v[210:213], v[46:49]
	v_mfma_f32_16x16x32_bf16 v[42:45], v[186:189], v[210:213], v[42:45]
	v_mfma_f32_16x16x32_bf16 v[38:41], v[178:181], v[218:221], v[38:41]
	v_mfma_f32_16x16x32_bf16 v[34:37], v[186:189], v[218:221], v[34:37]
	s_barrier
	s_add_u32 s16, s14, 0x8000
	s_addc_u32 s17, s15, 0
	s_add_i32 s46, s46, s22
	s_mov_b32 m0, s46
	ds_read_b128 v[190:193], v168 offset:49152
	ds_read_b128 v[194:197], v168 offset:50176
	ds_read_b128 v[198:201], v168 offset:51200
	ds_read_b128 v[202:205], v168 offset:52224
	ds_read_b128 v[206:209], v168 offset:53248
	ds_read_b128 v[210:213], v168 offset:54272
	ds_read_b128 v[214:217], v168 offset:55296
	ds_read_b128 v[218:221], v168 offset:56320
	global_load_lds_dwordx4 v142, s[16:17]
	s_add_i32 m0, s46, 0x2000
	s_add_u32 s14, s14, 0xc000
	v_lshl_add_u64 v[162:163], s[16:17], 0, v[138:139]
	s_addc_u32 s15, s15, 0
	s_add_i32 s16, s47, s22
	global_load_lds_dwordx4 v[162:163], off
	s_mov_b32 m0, s16
	s_nop 0
	global_load_lds_dwordx4 v142, s[14:15]
	s_add_i32 m0, s16, 0x2000
	s_nop 0
	global_load_lds_dwordx4 v138, s[14:15]
	s_waitcnt vmcnt(6)
	s_waitcnt lgkmcnt(0)
	s_barrier
	s_waitcnt lgkmcnt(0)
	v_mfma_f32_16x16x32_bf16 v[94:97], v[130:133], v[190:193], v[94:97]
	v_mfma_f32_16x16x32_bf16 v[90:93], v[158:161], v[190:193], v[90:93]
	v_mfma_f32_16x16x32_bf16 v[86:89], v[130:133], v[198:201], v[86:89]
	v_mfma_f32_16x16x32_bf16 v[82:85], v[158:161], v[198:201], v[82:85]
	v_mfma_f32_16x16x32_bf16 v[78:81], v[130:133], v[206:209], v[78:81]
	v_mfma_f32_16x16x32_bf16 v[74:77], v[158:161], v[206:209], v[74:77]
	v_mfma_f32_16x16x32_bf16 v[70:73], v[130:133], v[214:217], v[70:73]
	v_mfma_f32_16x16x32_bf16 v[66:69], v[158:161], v[214:217], v[66:69]
	v_mfma_f32_16x16x32_bf16 v[94:97], v[134:137], v[194:197], v[94:97]
	v_mfma_f32_16x16x32_bf16 v[90:93], v[170:173], v[194:197], v[90:93]
	v_mfma_f32_16x16x32_bf16 v[86:89], v[134:137], v[202:205], v[86:89]
	v_mfma_f32_16x16x32_bf16 v[82:85], v[170:173], v[202:205], v[82:85]
	v_mfma_f32_16x16x32_bf16 v[78:81], v[134:137], v[210:213], v[78:81]
	v_mfma_f32_16x16x32_bf16 v[74:77], v[170:173], v[210:213], v[74:77]
	v_mfma_f32_16x16x32_bf16 v[70:73], v[134:137], v[218:221], v[70:73]
	v_mfma_f32_16x16x32_bf16 v[66:69], v[170:173], v[218:221], v[66:69]
	v_mfma_f32_16x16x32_bf16 v[30:33], v[174:177], v[190:193], v[30:33]
	v_mfma_f32_16x16x32_bf16 v[26:29], v[182:185], v[190:193], v[26:29]
	v_mfma_f32_16x16x32_bf16 v[22:25], v[174:177], v[198:201], v[22:25]
	v_mfma_f32_16x16x32_bf16 v[18:21], v[182:185], v[198:201], v[18:21]
	v_mfma_f32_16x16x32_bf16 v[14:17], v[174:177], v[206:209], v[14:17]
	v_mfma_f32_16x16x32_bf16 v[10:13], v[182:185], v[206:209], v[10:13]
	v_mfma_f32_16x16x32_bf16 v[6:9], v[174:177], v[214:217], v[6:9]
	v_mfma_f32_16x16x32_bf16 v[2:5], v[182:185], v[214:217], v[2:5]
	v_mfma_f32_16x16x32_bf16 v[30:33], v[178:181], v[194:197], v[30:33]
	v_mfma_f32_16x16x32_bf16 v[26:29], v[186:189], v[194:197], v[26:29]
	v_mfma_f32_16x16x32_bf16 v[22:25], v[178:181], v[202:205], v[22:25]
	v_mfma_f32_16x16x32_bf16 v[18:21], v[186:189], v[202:205], v[18:21]
	v_mfma_f32_16x16x32_bf16 v[14:17], v[178:181], v[210:213], v[14:17]
	v_mfma_f32_16x16x32_bf16 v[10:13], v[186:189], v[210:213], v[10:13]
	v_mfma_f32_16x16x32_bf16 v[6:9], v[178:181], v[218:221], v[6:9]
	v_mfma_f32_16x16x32_bf16 v[2:5], v[186:189], v[218:221], v[2:5]
	s_add_i32 s45, s45, 2
	s_add_u32 s10, s10, 0x10000
	s_addc_u32 s11, s11, 0
	s_add_u32 s43, s43, 0x10000
	s_addc_u32 s44, s44, 0
	s_cmp_gt_u32 s45, 5
	s_barrier
	s_cbranch_scc0 .LBB0_2685
	s_and_b64 vcc, exec, s[6:7]
	s_cbranch_vccz .LBB0_2688
	s_barrier

; #define PG8_STAGE(bufoff, gbase, voff) do { _Pragma("unroll") for (int _i = 0; _i < 2; ++_i) \
;         __builtin_amdgcn_global_load_lds((const unsigned*)((const char*)(gbase) + (voff)[_i]), (LAS unsigned*)(lds + (bufoff) + ldsw + _i * 8192), 16, 0, 0); } while (0)
; #define PG8_LDA(dst, b, h) do { _Pragma("unroll") for (int m = 0; m < 4; ++m) _Pragma("unroll") for (int k = 0; k < 2; ++k) dst[m][k] = *(const LAS bf16x8*)(lds + PG8_SA(b, h) + aoff + m * 2048 + k * 1024); } while (0)
; #define PG8_LDB(dst, b, h) do { _Pragma("unroll") for (int n = 0; n < 2; ++n) _Pragma("unroll") for (int k = 0; k < 2; ++k) dst[n][k] = *(const LAS bf16x8*)(lds + PG8_SB(b, h) + boff + n * 2048 + k * 1024); } while (0)
; #define PG8_WAIT_V(n) asm volatile("s_waitcnt vmcnt(" #n ")" ::: "memory")
; #define PG8_WAIT_L(n) asm volatile("s_waitcnt lgkmcnt(" #n ")" ::: "memory")
; #define PG8_BAR __builtin_amdgcn_s_barrier()
; #define PG8_SCHED __builtin_amdgcn_sched_barrier(0)
; template <class Epi, class Sched, bool I8 = false>
; __device__ __forceinline__ void gemm_phase(LAS unsigned char* lds, const Gemm g, const Sched& S, const Epi& E) {
;     ...
;             PG8_LDB(B0, 0, 0); PG8_LDB(B1, 0, 1); PG8_SCHED; PG8_LDA(At, 0, 0); PG8_STAGE(PG8_SA(1, 1), a1 + hstepA, voffA);
;             PG8_WAIT_V(8); PG8_WAIT_L(0); PG8_BAR; PG8_MMA(0, 0, At, B0); PG8_MMA(0, 1, At, B1); PG8_BAR; PG8_SCHED;
;             PG8_LDA(At, 0, 1); PG8_STAGE(PG8_SB(0, 0), b2, voffB); PG8_STAGE(PG8_SB(0, 1), b2 + hstepB, voffB); PG8_STAGE(PG8_SA(0, 0), a2, voffA);
;             PG8_WAIT_V(8); PG8_WAIT_L(0); PG8_BAR; PG8_MMA(1, 0, At, B0); PG8_MMA(1, 1, At, B1); PG8_BAR; PG8_SCHED;
.LBB0_3744:
	ds_read_b128 v[130:133], v231
	ds_read_b128 v[134:137], v231 offset:1024
	ds_read_b128 v[138:141], v231 offset:2048
	ds_read_b128 v[142:145], v231 offset:3072
	ds_read_b128 v[146:149], v232
	ds_read_b128 v[150:153], v232 offset:1024
	ds_read_b128 v[154:157], v232 offset:2048
	ds_read_b128 v[158:161], v232 offset:3072
	s_add_u32 s34, s30, 0x4000
	s_addc_u32 s35, s31, 0
	s_cmp_eq_u32 s59, 60
	s_cselect_b32 s38, s23, s34
	s_cselect_b32 s39, s5, s35
	s_cselect_b32 s36, s29, s57
	s_cselect_b32 s37, s21, s58
	s_add_u32 s34, s38, 0x8000
	s_addc_u32 s35, s39, 0
	s_sub_u32 s98, s30, 0x4000
	s_subb_u32 s99, s31, 0
	s_mov_b32 m0, s51
	s_nop 0
	global_load_lds_dwordx4 v194, s[98:99]
	s_mov_b32 m0, s52
	s_nop 0
	global_load_lds_dwordx4 v198, s[98:99]
	s_add_i32 m0, s44, 0xc000
	ds_read_b128 v[162:165], v233
	ds_read_b128 v[166:169], v233 offset:1024
	ds_read_b128 v[170:173], v233 offset:2048
	ds_read_b128 v[174:177], v233 offset:3072
	ds_read_b128 v[178:181], v233 offset:4096
	ds_read_b128 v[182:185], v233 offset:5120
	ds_read_b128 v[186:189], v233 offset:6144
	ds_read_b128 v[190:193], v233 offset:7168
	global_load_lds_dwordx4 v204, s[30:31]
	s_add_i32 m0, s44, 0xe000
	s_nop 0
	global_load_lds_dwordx4 v206, s[30:31]
	s_waitcnt vmcnt(8)
	s_waitcnt lgkmcnt(0)
	s_barrier
	s_waitcnt lgkmcnt(0)
	v_mfma_f32_16x16x32_bf16 v[126:129], v[130:133], v[162:165], v[126:129]
	v_mfma_f32_16x16x32_bf16 v[122:125], v[138:141], v[162:165], v[122:125]
	v_mfma_f32_16x16x32_bf16 v[118:121], v[130:133], v[170:173], v[118:121]
	v_mfma_f32_16x16x32_bf16 v[110:113], v[138:141], v[170:173], v[110:113]
	v_mfma_f32_16x16x32_bf16 v[102:105], v[130:133], v[178:181], v[102:105]
	v_mfma_f32_16x16x32_bf16 v[94:97], v[138:141], v[178:181], v[94:97]
	v_mfma_f32_16x16x32_bf16 v[86:89], v[130:133], v[186:189], v[86:89]
	v_mfma_f32_16x16x32_bf16 v[78:81], v[138:141], v[186:189], v[78:81]
	v_mfma_f32_16x16x32_bf16 v[126:129], v[134:137], v[166:169], v[126:129]
	v_mfma_f32_16x16x32_bf16 v[122:125], v[142:145], v[166:169], v[122:125]
	v_mfma_f32_16x16x32_bf16 v[118:121], v[134:137], v[174:177], v[118:121]
	v_mfma_f32_16x16x32_bf16 v[110:113], v[142:145], v[174:177], v[110:113]
	v_mfma_f32_16x16x32_bf16 v[102:105], v[134:137], v[182:185], v[102:105]
	v_mfma_f32_16x16x32_bf16 v[94:97], v[142:145], v[182:185], v[94:97]
	v_mfma_f32_16x16x32_bf16 v[86:89], v[134:137], v[190:193], v[86:89]
	v_mfma_f32_16x16x32_bf16 v[78:81], v[142:145], v[190:193], v[78:81]
	v_mfma_f32_16x16x32_bf16 v[114:117], v[146:149], v[162:165], v[114:117]
	v_mfma_f32_16x16x32_bf16 v[106:109], v[154:157], v[162:165], v[106:109]
	v_mfma_f32_16x16x32_bf16 v[98:101], v[146:149], v[170:173], v[98:101]
	v_mfma_f32_16x16x32_bf16 v[90:93], v[154:157], v[170:173], v[90:93]
	v_mfma_f32_16x16x32_bf16 v[82:85], v[146:149], v[178:181], v[82:85]
	v_mfma_f32_16x16x32_bf16 v[74:77], v[154:157], v[178:181], v[74:77]
	v_mfma_f32_16x16x32_bf16 v[70:73], v[146:149], v[186:189], v[70:73]
	v_mfma_f32_16x16x32_bf16 v[66:69], v[154:157], v[186:189], v[66:69]
	v_mfma_f32_16x16x32_bf16 v[114:117], v[150:153], v[166:169], v[114:117]
	v_mfma_f32_16x16x32_bf16 v[106:109], v[158:161], v[166:169], v[106:109]
	v_mfma_f32_16x16x32_bf16 v[98:101], v[150:153], v[174:177], v[98:101]
	v_mfma_f32_16x16x32_bf16 v[90:93], v[158:161], v[174:177], v[90:93]
	v_mfma_f32_16x16x32_bf16 v[82:85], v[150:153], v[182:185], v[82:85]
	v_mfma_f32_16x16x32_bf16 v[74:77], v[158:161], v[182:185], v[74:77]
	v_mfma_f32_16x16x32_bf16 v[70:73], v[150:153], v[190:193], v[70:73]
	v_mfma_f32_16x16x32_bf16 v[66:69], v[158:161], v[190:193], v[66:69]
	s_barrier
	s_add_i32 s60, s55, s43
	s_mov_b32 m0, s60
	ds_read_b128 v[162:165], v233 offset:16384
	ds_read_b128 v[166:169], v233 offset:17408
	ds_read_b128 v[170:173], v233 offset:18432
	ds_read_b128 v[174:177], v233 offset:19456
	ds_read_b128 v[178:181], v233 offset:20480
	ds_read_b128 v[182:185], v233 offset:21504
	ds_read_b128 v[186:189], v233 offset:22528
	ds_read_b128 v[190:193], v233 offset:23552
	global_load_lds_dwordx4 v196, s[36:37]
	s_add_i32 m0, s60, 0x2000
	s_add_u32 s60, s36, 0x4000
	s_addc_u32 s61, s37, 0
	s_add_i32 s62, s56, s43
	global_load_lds_dwordx4 v200, s[36:37]
	s_mov_b32 m0, s62
	s_nop 0
	global_load_lds_dwordx4 v196, s[60:61]
	s_add_i32 m0, s62, 0x2000
	s_nop 0
	global_load_lds_dwordx4 v200, s[60:61]
	s_waitcnt vmcnt(6)
	s_waitcnt lgkmcnt(0)
	s_barrier
	s_waitcnt lgkmcnt(0)
	v_mfma_f32_16x16x32_bf16 v[62:65], v[130:133], v[162:165], v[62:65]
	v_mfma_f32_16x16x32_bf16 v[58:61], v[138:141], v[162:165], v[58:61]
	v_mfma_f32_16x16x32_bf16 v[54:57], v[130:133], v[170:173], v[54:57]
	v_mfma_f32_16x16x32_bf16 v[46:49], v[138:141], v[170:173], v[46:49]
	v_mfma_f32_16x16x32_bf16 v[38:41], v[130:133], v[178:181], v[38:41]
	v_mfma_f32_16x16x32_bf16 v[30:33], v[138:141], v[178:181], v[30:33]
	v_mfma_f32_16x16x32_bf16 v[22:25], v[130:133], v[186:189], v[22:25]
	v_mfma_f32_16x16x32_bf16 v[14:17], v[138:141], v[186:189], v[14:17]
	v_mfma_f32_16x16x32_bf16 v[62:65], v[134:137], v[166:169], v[62:65]
	v_mfma_f32_16x16x32_bf16 v[58:61], v[142:145], v[166:169], v[58:61]
	v_mfma_f32_16x16x32_bf16 v[54:57], v[134:137], v[174:177], v[54:57]
	v_mfma_f32_16x16x32_bf16 v[46:49], v[142:145], v[174:177], v[46:49]
	v_mfma_f32_16x16x32_bf16 v[38:41], v[134:137], v[182:185], v[38:41]
	v_mfma_f32_16x16x32_bf16 v[30:33], v[142:145], v[182:185], v[30:33]
	v_mfma_f32_16x16x32_bf16 v[22:25], v[134:137], v[190:193], v[22:25]
	v_mfma_f32_16x16x32_bf16 v[14:17], v[142:145], v[190:193], v[14:17]
	v_mfma_f32_16x16x32_bf16 v[50:53], v[146:149], v[162:165], v[50:53]
	v_mfma_f32_16x16x32_bf16 v[42:45], v[154:157], v[162:165], v[42:45]
	v_mfma_f32_16x16x32_bf16 v[34:37], v[146:149], v[170:173], v[34:37]
	v_mfma_f32_16x16x32_bf16 v[26:29], v[154:157], v[170:173], v[26:29]
	v_mfma_f32_16x16x32_bf16 v[18:21], v[146:149], v[178:181], v[18:21]
	v_mfma_f32_16x16x32_bf16 v[10:13], v[154:157], v[178:181], v[10:13]
	v_mfma_f32_16x16x32_bf16 v[6:9], v[146:149], v[186:189], v[6:9]
	v_mfma_f32_16x16x32_bf16 v[2:5], v[154:157], v[186:189], v[2:5]
	v_mfma_f32_16x16x32_bf16 v[50:53], v[150:153], v[166:169], v[50:53]
	v_mfma_f32_16x16x32_bf16 v[42:45], v[158:161], v[166:169], v[42:45]
	v_mfma_f32_16x16x32_bf16 v[34:37], v[150:153], v[174:177], v[34:37]
	v_mfma_f32_16x16x32_bf16 v[26:29], v[158:161], v[174:177], v[26:29]
	v_mfma_f32_16x16x32_bf16 v[18:21], v[150:153], v[182:185], v[18:21]
	v_mfma_f32_16x16x32_bf16 v[10:13], v[158:161], v[182:185], v[10:13]
	v_mfma_f32_16x16x32_bf16 v[6:9], v[150:153], v[190:193], v[6:9]
	v_mfma_f32_16x16x32_bf16 v[2:5], v[158:161], v[190:193], v[2:5]
	s_barrier
; #define PG8_STAGE(bufoff, gbase, voff) do { _Pragma("unroll") for (int _i = 0; _i < 2; ++_i) \
;         __builtin_amdgcn_global_load_lds((const unsigned*)((const char*)(gbase) + (voff)[_i]), (LAS unsigned*)(lds + (bufoff) + ldsw + _i * 8192), 16, 0, 0); } while (0)
; #define PG8_LDA(dst, b, h) do { _Pragma("unroll") for (int m = 0; m < 4; ++m) _Pragma("unroll") for (int k = 0; k < 2; ++k) dst[m][k] = *(const LAS bf16x8*)(lds + PG8_SA(b, h) + aoff + m * 2048 + k * 1024); } while (0)
; #define PG8_LDB(dst, b, h) do { _Pragma("unroll") for (int n = 0; n < 2; ++n) _Pragma("unroll") for (int k = 0; k < 2; ++k) dst[n][k] = *(const LAS bf16x8*)(lds + PG8_SB(b, h) + boff + n * 2048 + k * 1024); } while (0)
; #define PG8_WAIT_V(n) asm volatile("s_waitcnt vmcnt(" #n ")" ::: "memory")
; #define PG8_WAIT_L(n) asm volatile("s_waitcnt lgkmcnt(" #n ")" ::: "memory")
; #define PG8_BAR __builtin_amdgcn_s_barrier()
; #define PG8_SCHED __builtin_amdgcn_sched_barrier(0)
; template <class Epi, class Sched, bool I8 = false>
; __device__ __forceinline__ void gemm_phase(LAS unsigned char* lds, const Gemm g, const Sched& S, const Epi& E) {
;     ...
;             PG8_LDB(B0, 1, 0); PG8_LDB(B1, 1, 1); PG8_SCHED; PG8_LDA(At, 1, 0); PG8_STAGE(PG8_SA(0, 1), a2 + hstepA, voffA);
;             PG8_WAIT_V(8); PG8_WAIT_L(0); PG8_BAR; PG8_MMA(0, 0, At, B0); PG8_MMA(0, 1, At, B1); PG8_BAR; PG8_SCHED;
;             PG8_LDA(At, 1, 1); PG8_STAGE(PG8_SB(1, 0), b3, voffB); PG8_STAGE(PG8_SB(1, 1), b3 + hstepB, voffB); PG8_STAGE(PG8_SA(1, 0), a3, voffA);
;             PG8_WAIT_V(8); PG8_WAIT_L(0); PG8_BAR; PG8_MMA(1, 0, At, B0); PG8_MMA(1, 1, At, B1); PG8_BAR; PG8_SCHED;
	s_add_i32 s60, 0, 0x18000
	s_add_i32 s61, 0, 0x1c000
	v_add_u32_e32 v142, s60, v230
	v_add_u32_e32 v158, s61, v230
	ds_read_b128 v[130:133], v142
	ds_read_b128 v[134:137], v142 offset:1024
	ds_read_b128 v[138:141], v142 offset:2048
	ds_read_b128 v[142:145], v142 offset:3072
	ds_read_b128 v[146:149], v158
	ds_read_b128 v[150:153], v158 offset:1024
	ds_read_b128 v[154:157], v158 offset:2048
	ds_read_b128 v[158:161], v158 offset:3072
	s_mov_b32 m0, s44
	s_nop 0
	global_load_lds_dwordx4 v194, s[38:39]
	s_mov_b32 m0, s45
	s_nop 0
	global_load_lds_dwordx4 v198, s[38:39]
	s_add_u32 s38, s38, 0x4000
	s_addc_u32 s39, s39, 0
	s_mov_b32 m0, s46
	ds_read_b128 v[162:165], v233 offset:32768
	ds_read_b128 v[166:169], v233 offset:33792
	ds_read_b128 v[170:173], v233 offset:34816
	ds_read_b128 v[174:177], v233 offset:35840
	ds_read_b128 v[178:181], v233 offset:36864
	ds_read_b128 v[182:185], v233 offset:37888
	ds_read_b128 v[186:189], v233 offset:38912
	ds_read_b128 v[190:193], v233 offset:39936
	global_load_lds_dwordx4 v194, s[38:39]
	s_mov_b32 m0, s47
	s_nop 0
	global_load_lds_dwordx4 v198, s[38:39]
	s_waitcnt vmcnt(8)
	s_waitcnt lgkmcnt(0)
	s_barrier
	s_waitcnt lgkmcnt(0)
	v_mfma_f32_16x16x32_bf16 v[126:129], v[130:133], v[162:165], v[126:129]
	v_mfma_f32_16x16x32_bf16 v[122:125], v[138:141], v[162:165], v[122:125]
	v_mfma_f32_16x16x32_bf16 v[118:121], v[130:133], v[170:173], v[118:121]
	v_mfma_f32_16x16x32_bf16 v[110:113], v[138:141], v[170:173], v[110:113]
	v_mfma_f32_16x16x32_bf16 v[102:105], v[130:133], v[178:181], v[102:105]
	v_mfma_f32_16x16x32_bf16 v[94:97], v[138:141], v[178:181], v[94:97]
	v_mfma_f32_16x16x32_bf16 v[86:89], v[130:133], v[186:189], v[86:89]
	v_mfma_f32_16x16x32_bf16 v[78:81], v[138:141], v[186:189], v[78:81]
	v_mfma_f32_16x16x32_bf16 v[126:129], v[134:137], v[166:169], v[126:129]
	v_mfma_f32_16x16x32_bf16 v[122:125], v[142:145], v[166:169], v[122:125]
	v_mfma_f32_16x16x32_bf16 v[118:121], v[134:137], v[174:177], v[118:121]
	v_mfma_f32_16x16x32_bf16 v[110:113], v[142:145], v[174:177], v[110:113]
	v_mfma_f32_16x16x32_bf16 v[102:105], v[134:137], v[182:185], v[102:105]
	v_mfma_f32_16x16x32_bf16 v[94:97], v[142:145], v[182:185], v[94:97]
	v_mfma_f32_16x16x32_bf16 v[86:89], v[134:137], v[190:193], v[86:89]
	v_mfma_f32_16x16x32_bf16 v[78:81], v[142:145], v[190:193], v[78:81]
	v_mfma_f32_16x16x32_bf16 v[114:117], v[146:149], v[162:165], v[114:117]
	v_mfma_f32_16x16x32_bf16 v[106:109], v[154:157], v[162:165], v[106:109]
	v_mfma_f32_16x16x32_bf16 v[98:101], v[146:149], v[170:173], v[98:101]
	v_mfma_f32_16x16x32_bf16 v[90:93], v[154:157], v[170:173], v[90:93]
	v_mfma_f32_16x16x32_bf16 v[82:85], v[146:149], v[178:181], v[82:85]
	v_mfma_f32_16x16x32_bf16 v[74:77], v[154:157], v[178:181], v[74:77]
	v_mfma_f32_16x16x32_bf16 v[70:73], v[146:149], v[186:189], v[70:73]
	v_mfma_f32_16x16x32_bf16 v[66:69], v[154:157], v[186:189], v[66:69]
	v_mfma_f32_16x16x32_bf16 v[114:117], v[150:153], v[166:169], v[114:117]
	v_mfma_f32_16x16x32_bf16 v[106:109], v[158:161], v[166:169], v[106:109]
	v_mfma_f32_16x16x32_bf16 v[98:101], v[150:153], v[174:177], v[98:101]
	v_mfma_f32_16x16x32_bf16 v[90:93], v[158:161], v[174:177], v[90:93]
	v_mfma_f32_16x16x32_bf16 v[82:85], v[150:153], v[182:185], v[82:85]
	v_mfma_f32_16x16x32_bf16 v[74:77], v[158:161], v[182:185], v[74:77]
	v_mfma_f32_16x16x32_bf16 v[70:73], v[150:153], v[190:193], v[70:73]
	v_mfma_f32_16x16x32_bf16 v[66:69], v[158:161], v[190:193], v[66:69]
	s_barrier
	s_add_u32 s38, s36, 0x8000
	s_addc_u32 s39, s37, 0
	s_add_i32 s60, s60, s43
	s_mov_b32 m0, s60
	ds_read_b128 v[162:165], v233 offset:49152
	ds_read_b128 v[166:169], v233 offset:50176
	ds_read_b128 v[170:173], v233 offset:51200
	ds_read_b128 v[174:177], v233 offset:52224
	ds_read_b128 v[178:181], v233 offset:53248
	ds_read_b128 v[182:185], v233 offset:54272
	ds_read_b128 v[186:189], v233 offset:55296
	ds_read_b128 v[190:193], v233 offset:56320
	global_load_lds_dwordx4 v196, s[38:39]
	s_add_i32 m0, s60, 0x2000
	s_add_u32 s36, s36, 0xc000
	v_lshl_add_u64 v[212:213], s[38:39], 0, v[200:201]
	s_addc_u32 s37, s37, 0
	s_add_i32 s38, s61, s43
	global_load_lds_dwordx4 v[212:213], off
	s_mov_b32 m0, s38
	s_nop 0
	global_load_lds_dwordx4 v196, s[36:37]
	s_add_i32 m0, s38, 0x2000
	s_nop 0
	global_load_lds_dwordx4 v200, s[36:37]
	s_waitcnt vmcnt(6)
	s_waitcnt lgkmcnt(0)
	s_barrier
	s_waitcnt lgkmcnt(0)
	v_mfma_f32_16x16x32_bf16 v[62:65], v[130:133], v[162:165], v[62:65]
	v_mfma_f32_16x16x32_bf16 v[58:61], v[138:141], v[162:165], v[58:61]
	v_mfma_f32_16x16x32_bf16 v[54:57], v[130:133], v[170:173], v[54:57]
	v_mfma_f32_16x16x32_bf16 v[46:49], v[138:141], v[170:173], v[46:49]
	v_mfma_f32_16x16x32_bf16 v[38:41], v[130:133], v[178:181], v[38:41]
	v_mfma_f32_16x16x32_bf16 v[30:33], v[138:141], v[178:181], v[30:33]
	v_mfma_f32_16x16x32_bf16 v[22:25], v[130:133], v[186:189], v[22:25]
	v_mfma_f32_16x16x32_bf16 v[14:17], v[138:141], v[186:189], v[14:17]
	v_mfma_f32_16x16x32_bf16 v[62:65], v[134:137], v[166:169], v[62:65]
	v_mfma_f32_16x16x32_bf16 v[58:61], v[142:145], v[166:169], v[58:61]
	v_mfma_f32_16x16x32_bf16 v[54:57], v[134:137], v[174:177], v[54:57]
	v_mfma_f32_16x16x32_bf16 v[46:49], v[142:145], v[174:177], v[46:49]
	v_mfma_f32_16x16x32_bf16 v[38:41], v[134:137], v[182:185], v[38:41]
	v_mfma_f32_16x16x32_bf16 v[30:33], v[142:145], v[182:185], v[30:33]
	v_mfma_f32_16x16x32_bf16 v[22:25], v[134:137], v[190:193], v[22:25]
	v_mfma_f32_16x16x32_bf16 v[14:17], v[142:145], v[190:193], v[14:17]
	v_mfma_f32_16x16x32_bf16 v[50:53], v[146:149], v[162:165], v[50:53]
	v_mfma_f32_16x16x32_bf16 v[42:45], v[154:157], v[162:165], v[42:45]
	v_mfma_f32_16x16x32_bf16 v[34:37], v[146:149], v[170:173], v[34:37]
	v_mfma_f32_16x16x32_bf16 v[26:29], v[154:157], v[170:173], v[26:29]
	v_mfma_f32_16x16x32_bf16 v[18:21], v[146:149], v[178:181], v[18:21]
	v_mfma_f32_16x16x32_bf16 v[10:13], v[154:157], v[178:181], v[10:13]
	v_mfma_f32_16x16x32_bf16 v[6:9], v[146:149], v[186:189], v[6:9]
	v_mfma_f32_16x16x32_bf16 v[2:5], v[154:157], v[186:189], v[2:5]
	v_mfma_f32_16x16x32_bf16 v[50:53], v[150:153], v[166:169], v[50:53]
	v_mfma_f32_16x16x32_bf16 v[42:45], v[158:161], v[166:169], v[42:45]
	v_mfma_f32_16x16x32_bf16 v[34:37], v[150:153], v[174:177], v[34:37]
	v_mfma_f32_16x16x32_bf16 v[26:29], v[158:161], v[174:177], v[26:29]
	v_mfma_f32_16x16x32_bf16 v[18:21], v[150:153], v[182:185], v[18:21]
	v_mfma_f32_16x16x32_bf16 v[10:13], v[158:161], v[182:185], v[10:13]
	v_mfma_f32_16x16x32_bf16 v[6:9], v[150:153], v[190:193], v[6:9]
	v_mfma_f32_16x16x32_bf16 v[2:5], v[158:161], v[190:193], v[2:5]
	s_add_i32 s59, s59, 2
	s_add_u32 s30, s30, 0x10000
	s_addc_u32 s31, s31, 0
	s_add_u32 s57, s57, 0x10000
	s_addc_u32 s58, s58, 0
	s_cmp_gt_u32 s59, 61
	s_barrier
	s_cbranch_scc0 .LBB0_3744
	s_and_b64 vcc, exec, s[6:7]
	s_cbranch_vccz .LBB0_3747
	s_barrier

; #define PG8_STAGE(bufoff, gbase, voff) do { _Pragma("unroll") for (int _i = 0; _i < 2; ++_i) \
;         __builtin_amdgcn_global_load_lds((const unsigned*)((const char*)(gbase) + (voff)[_i]), (LAS unsigned*)(lds + (bufoff) + ldsw + _i * 8192), 16, 0, 0); } while (0)
; #define PG8_LDA(dst, b, h) do { _Pragma("unroll") for (int m = 0; m < 4; ++m) _Pragma("unroll") for (int k = 0; k < 2; ++k) dst[m][k] = *(const LAS bf16x8*)(lds + PG8_SA(b, h) + aoff + m * 2048 + k * 1024); } while (0)
; #define PG8_LDB(dst, b, h) do { _Pragma("unroll") for (int n = 0; n < 2; ++n) _Pragma("unroll") for (int k = 0; k < 2; ++k) dst[n][k] = *(const LAS bf16x8*)(lds + PG8_SB(b, h) + boff + n * 2048 + k * 1024); } while (0)
; #define PG8_WAIT_V(n) asm volatile("s_waitcnt vmcnt(" #n ")" ::: "memory")
; #define PG8_WAIT_L(n) asm volatile("s_waitcnt lgkmcnt(" #n ")" ::: "memory")
; #define PG8_BAR __builtin_amdgcn_s_barrier()
; #define PG8_SCHED __builtin_amdgcn_sched_barrier(0)
; template <class Epi, class Sched, bool I8 = false>
; __device__ __forceinline__ void gemm_phase(LAS unsigned char* lds, const Gemm g, const Sched& S, const Epi& E) {
;     ...
;             PG8_LDB(B0, 0, 0); PG8_LDB(B1, 0, 1); PG8_SCHED; PG8_LDA(At, 0, 0); PG8_STAGE(PG8_SA(1, 1), a1 + hstepA, voffA);
;             PG8_WAIT_V(8); PG8_WAIT_L(0); PG8_BAR; PG8_MMA(0, 0, At, B0); PG8_MMA(0, 1, At, B1); PG8_BAR; PG8_SCHED;
;             PG8_LDA(At, 0, 1); PG8_STAGE(PG8_SB(0, 0), b2, voffB); PG8_STAGE(PG8_SB(0, 1), b2 + hstepB, voffB); PG8_STAGE(PG8_SA(0, 0), a2, voffA);
;             PG8_WAIT_V(8); PG8_WAIT_L(0); PG8_BAR; PG8_MMA(1, 0, At, B0); PG8_MMA(1, 1, At, B1); PG8_BAR; PG8_SCHED;
.LBB0_4168:
	ds_read_b128 v[66:69], v178
	ds_read_b128 v[70:73], v178 offset:1024
	ds_read_b128 v[74:77], v178 offset:2048
	ds_read_b128 v[78:81], v178 offset:3072
	ds_read_b128 v[146:149], v179
	ds_read_b128 v[150:153], v179 offset:1024
	ds_read_b128 v[172:175], v179 offset:2048
	ds_read_b128 v[182:185], v179 offset:3072
	s_add_u32 s22, s20, 0x4000
	s_addc_u32 s23, s21, 0
	s_cmpk_eq_i32 s51, 0x52
	s_cselect_b32 s26, s0, s22
	s_cselect_b32 s27, s1, s23
	s_cselect_b32 s24, s18, s49
	s_cselect_b32 s25, s19, s50
	s_add_u32 s22, s26, 0x8000
	s_addc_u32 s23, s27, 0
	s_sub_u32 s98, s20, 0x4000
	s_subb_u32 s99, s21, 0
	s_mov_b32 m0, s39
	s_nop 0
	global_load_lds_dwordx4 v154, s[98:99]
	s_mov_b32 m0, s40
	s_nop 0
	global_load_lds_dwordx4 v158, s[98:99]
	s_add_i32 m0, s34, 0xc000
	ds_read_b128 v[186:189], v180
	ds_read_b128 v[190:193], v180 offset:1024
	ds_read_b128 v[194:197], v180 offset:2048
	ds_read_b128 v[198:201], v180 offset:3072
	ds_read_b128 v[202:205], v180 offset:4096
	ds_read_b128 v[206:209], v180 offset:5120
	ds_read_b128 v[210:213], v180 offset:6144
	ds_read_b128 v[214:217], v180 offset:7168
	global_load_lds_dwordx4 v164, s[20:21]
	s_add_i32 m0, s34, 0xe000
	s_nop 0
	global_load_lds_dwordx4 v166, s[20:21]
	s_waitcnt vmcnt(8)
	s_waitcnt lgkmcnt(0)
	s_barrier
	s_waitcnt lgkmcnt(0)
	v_mfma_i32_16x16x64_i8 v[142:145], v[66:69], v[186:189], v[142:145]
	v_mfma_i32_16x16x64_i8 v[138:141], v[74:77], v[186:189], v[138:141]
	v_mfma_i32_16x16x64_i8 v[126:129], v[66:69], v[194:197], v[126:129]
	v_mfma_i32_16x16x64_i8 v[122:125], v[74:77], v[194:197], v[122:125]
	v_mfma_i32_16x16x64_i8 v[110:113], v[66:69], v[202:205], v[110:113]
	v_mfma_i32_16x16x64_i8 v[106:109], v[74:77], v[202:205], v[106:109]
	v_mfma_i32_16x16x64_i8 v[94:97], v[66:69], v[210:213], v[94:97]
	v_mfma_i32_16x16x64_i8 v[90:93], v[74:77], v[210:213], v[90:93]
	v_mfma_i32_16x16x64_i8 v[142:145], v[70:73], v[190:193], v[142:145]
	v_mfma_i32_16x16x64_i8 v[138:141], v[78:81], v[190:193], v[138:141]
	v_mfma_i32_16x16x64_i8 v[126:129], v[70:73], v[198:201], v[126:129]
	v_mfma_i32_16x16x64_i8 v[122:125], v[78:81], v[198:201], v[122:125]
	v_mfma_i32_16x16x64_i8 v[110:113], v[70:73], v[206:209], v[110:113]
	v_mfma_i32_16x16x64_i8 v[106:109], v[78:81], v[206:209], v[106:109]
	v_mfma_i32_16x16x64_i8 v[94:97], v[70:73], v[214:217], v[94:97]
	v_mfma_i32_16x16x64_i8 v[90:93], v[78:81], v[214:217], v[90:93]
	v_mfma_i32_16x16x64_i8 v[134:137], v[146:149], v[186:189], v[134:137]
	v_mfma_i32_16x16x64_i8 v[130:133], v[172:175], v[186:189], v[130:133]
	v_mfma_i32_16x16x64_i8 v[118:121], v[146:149], v[194:197], v[118:121]
	v_mfma_i32_16x16x64_i8 v[114:117], v[172:175], v[194:197], v[114:117]
	v_mfma_i32_16x16x64_i8 v[102:105], v[146:149], v[202:205], v[102:105]
	v_mfma_i32_16x16x64_i8 v[98:101], v[172:175], v[202:205], v[98:101]
	v_mfma_i32_16x16x64_i8 v[86:89], v[146:149], v[210:213], v[86:89]
	v_mfma_i32_16x16x64_i8 v[82:85], v[172:175], v[210:213], v[82:85]
	v_mfma_i32_16x16x64_i8 v[134:137], v[150:153], v[190:193], v[134:137]
	v_mfma_i32_16x16x64_i8 v[130:133], v[182:185], v[190:193], v[130:133]
	v_mfma_i32_16x16x64_i8 v[118:121], v[150:153], v[198:201], v[118:121]
	v_mfma_i32_16x16x64_i8 v[114:117], v[182:185], v[198:201], v[114:117]
	v_mfma_i32_16x16x64_i8 v[102:105], v[150:153], v[206:209], v[102:105]
	v_mfma_i32_16x16x64_i8 v[98:101], v[182:185], v[206:209], v[98:101]
	v_mfma_i32_16x16x64_i8 v[86:89], v[150:153], v[214:217], v[86:89]
	v_mfma_i32_16x16x64_i8 v[82:85], v[182:185], v[214:217], v[82:85]
	s_barrier
	s_add_i32 s52, s43, s33
	s_mov_b32 m0, s52
	ds_read_b128 v[186:189], v180 offset:16384
	ds_read_b128 v[190:193], v180 offset:17408
	ds_read_b128 v[194:197], v180 offset:18432
	ds_read_b128 v[198:201], v180 offset:19456
	ds_read_b128 v[202:205], v180 offset:20480
	ds_read_b128 v[206:209], v180 offset:21504
	ds_read_b128 v[210:213], v180 offset:22528
	ds_read_b128 v[214:217], v180 offset:23552
	global_load_lds_dwordx4 v156, s[24:25]
	s_add_i32 m0, s52, 0x2000
	s_add_u32 s52, s24, 0x4000
	s_addc_u32 s53, s25, 0
	s_add_i32 s54, s44, s33
	global_load_lds_dwordx4 v160, s[24:25]
	s_mov_b32 m0, s54
	s_nop 0
	global_load_lds_dwordx4 v156, s[52:53]
	s_add_i32 m0, s54, 0x2000
	s_nop 0
	global_load_lds_dwordx4 v160, s[52:53]
	s_waitcnt vmcnt(6)
	s_waitcnt lgkmcnt(0)
	s_barrier
	s_waitcnt lgkmcnt(0)
	v_mfma_i32_16x16x64_i8 v[62:65], v[66:69], v[186:189], v[62:65]
	v_mfma_i32_16x16x64_i8 v[58:61], v[74:77], v[186:189], v[58:61]
	v_mfma_i32_16x16x64_i8 v[46:49], v[66:69], v[194:197], v[46:49]
	v_mfma_i32_16x16x64_i8 v[42:45], v[74:77], v[194:197], v[42:45]
	v_mfma_i32_16x16x64_i8 v[30:33], v[66:69], v[202:205], v[30:33]
	v_mfma_i32_16x16x64_i8 v[26:29], v[74:77], v[202:205], v[26:29]
	v_mfma_i32_16x16x64_i8 v[14:17], v[66:69], v[210:213], v[14:17]
	v_mfma_i32_16x16x64_i8 v[10:13], v[74:77], v[210:213], v[10:13]
	v_mfma_i32_16x16x64_i8 v[62:65], v[70:73], v[190:193], v[62:65]
	v_mfma_i32_16x16x64_i8 v[58:61], v[78:81], v[190:193], v[58:61]
	v_mfma_i32_16x16x64_i8 v[46:49], v[70:73], v[198:201], v[46:49]
	v_mfma_i32_16x16x64_i8 v[42:45], v[78:81], v[198:201], v[42:45]
	v_mfma_i32_16x16x64_i8 v[30:33], v[70:73], v[206:209], v[30:33]
	v_mfma_i32_16x16x64_i8 v[26:29], v[78:81], v[206:209], v[26:29]
	v_mfma_i32_16x16x64_i8 v[14:17], v[70:73], v[214:217], v[14:17]
	v_mfma_i32_16x16x64_i8 v[10:13], v[78:81], v[214:217], v[10:13]
	v_mfma_i32_16x16x64_i8 v[54:57], v[146:149], v[186:189], v[54:57]
	v_mfma_i32_16x16x64_i8 v[50:53], v[172:175], v[186:189], v[50:53]
	v_mfma_i32_16x16x64_i8 v[38:41], v[146:149], v[194:197], v[38:41]
	v_mfma_i32_16x16x64_i8 v[34:37], v[172:175], v[194:197], v[34:37]
	v_mfma_i32_16x16x64_i8 v[22:25], v[146:149], v[202:205], v[22:25]
	v_mfma_i32_16x16x64_i8 v[18:21], v[172:175], v[202:205], v[18:21]
	v_mfma_i32_16x16x64_i8 v[6:9], v[146:149], v[210:213], v[6:9]
	v_mfma_i32_16x16x64_i8 v[2:5], v[172:175], v[210:213], v[2:5]
	v_mfma_i32_16x16x64_i8 v[54:57], v[150:153], v[190:193], v[54:57]
	v_mfma_i32_16x16x64_i8 v[50:53], v[182:185], v[190:193], v[50:53]
	v_mfma_i32_16x16x64_i8 v[38:41], v[150:153], v[198:201], v[38:41]
	v_mfma_i32_16x16x64_i8 v[34:37], v[182:185], v[198:201], v[34:37]
	v_mfma_i32_16x16x64_i8 v[22:25], v[150:153], v[206:209], v[22:25]
	v_mfma_i32_16x16x64_i8 v[18:21], v[182:185], v[206:209], v[18:21]
	v_mfma_i32_16x16x64_i8 v[6:9], v[150:153], v[214:217], v[6:9]
	v_mfma_i32_16x16x64_i8 v[2:5], v[182:185], v[214:217], v[2:5]
	s_barrier
; #define PG8_STAGE(bufoff, gbase, voff) do { _Pragma("unroll") for (int _i = 0; _i < 2; ++_i) \
;         __builtin_amdgcn_global_load_lds((const unsigned*)((const char*)(gbase) + (voff)[_i]), (LAS unsigned*)(lds + (bufoff) + ldsw + _i * 8192), 16, 0, 0); } while (0)
; #define PG8_LDA(dst, b, h) do { _Pragma("unroll") for (int m = 0; m < 4; ++m) _Pragma("unroll") for (int k = 0; k < 2; ++k) dst[m][k] = *(const LAS bf16x8*)(lds + PG8_SA(b, h) + aoff + m * 2048 + k * 1024); } while (0)
; #define PG8_LDB(dst, b, h) do { _Pragma("unroll") for (int n = 0; n < 2; ++n) _Pragma("unroll") for (int k = 0; k < 2; ++k) dst[n][k] = *(const LAS bf16x8*)(lds + PG8_SB(b, h) + boff + n * 2048 + k * 1024); } while (0)
; #define PG8_WAIT_V(n) asm volatile("s_waitcnt vmcnt(" #n ")" ::: "memory")
; #define PG8_WAIT_L(n) asm volatile("s_waitcnt lgkmcnt(" #n ")" ::: "memory")
; #define PG8_BAR __builtin_amdgcn_s_barrier()
; #define PG8_SCHED __builtin_amdgcn_sched_barrier(0)
; template <class Epi, class Sched, bool I8 = false>
; __device__ __forceinline__ void gemm_phase(LAS unsigned char* lds, const Gemm g, const Sched& S, const Epi& E) {
;     ...
;             PG8_LDB(B0, 1, 0); PG8_LDB(B1, 1, 1); PG8_SCHED; PG8_LDA(At, 1, 0); PG8_STAGE(PG8_SA(0, 1), a2 + hstepA, voffA);
;             PG8_WAIT_V(8); PG8_WAIT_L(0); PG8_BAR; PG8_MMA(0, 0, At, B0); PG8_MMA(0, 1, At, B1); PG8_BAR; PG8_SCHED;
;             PG8_LDA(At, 1, 1); PG8_STAGE(PG8_SB(1, 0), b3, voffB); PG8_STAGE(PG8_SB(1, 1), b3 + hstepB, voffB); PG8_STAGE(PG8_SA(1, 0), a3, voffA);
;             PG8_WAIT_V(8); PG8_WAIT_L(0); PG8_BAR; PG8_MMA(1, 0, At, B0); PG8_MMA(1, 1, At, B1); PG8_BAR; PG8_SCHED;
	s_add_i32 s52, 0, 0x18000
	s_add_i32 s53, 0, 0x1c000
	v_add_u32_e32 v78, s52, v176
	v_add_u32_e32 v162, s53, v176
	ds_read_b128 v[66:69], v78
	ds_read_b128 v[70:73], v78 offset:1024
	ds_read_b128 v[74:77], v78 offset:2048
	ds_read_b128 v[78:81], v78 offset:3072
	ds_read_b128 v[146:149], v162
	ds_read_b128 v[150:153], v162 offset:1024
	ds_read_b128 v[172:175], v162 offset:2048
	ds_read_b128 v[182:185], v162 offset:3072
	s_mov_b32 m0, s34
	s_nop 0
	global_load_lds_dwordx4 v154, s[26:27]
	s_mov_b32 m0, s35
	s_nop 0
	global_load_lds_dwordx4 v158, s[26:27]
	s_add_u32 s26, s26, 0x4000
	s_addc_u32 s27, s27, 0
	s_mov_b32 m0, s36
	ds_read_b128 v[186:189], v180 offset:32768
	ds_read_b128 v[190:193], v180 offset:33792
	ds_read_b128 v[194:197], v180 offset:34816
	ds_read_b128 v[198:201], v180 offset:35840
	ds_read_b128 v[202:205], v180 offset:36864
	ds_read_b128 v[206:209], v180 offset:37888
	ds_read_b128 v[210:213], v180 offset:38912
	ds_read_b128 v[214:217], v180 offset:39936
	global_load_lds_dwordx4 v154, s[26:27]
	s_mov_b32 m0, s37
	s_nop 0
	global_load_lds_dwordx4 v158, s[26:27]
	s_waitcnt vmcnt(8)
	s_waitcnt lgkmcnt(0)
	s_barrier
	s_waitcnt lgkmcnt(0)
	v_mfma_i32_16x16x64_i8 v[142:145], v[66:69], v[186:189], v[142:145]
	v_mfma_i32_16x16x64_i8 v[138:141], v[74:77], v[186:189], v[138:141]
	v_mfma_i32_16x16x64_i8 v[126:129], v[66:69], v[194:197], v[126:129]
	v_mfma_i32_16x16x64_i8 v[122:125], v[74:77], v[194:197], v[122:125]
	v_mfma_i32_16x16x64_i8 v[110:113], v[66:69], v[202:205], v[110:113]
	v_mfma_i32_16x16x64_i8 v[106:109], v[74:77], v[202:205], v[106:109]
	v_mfma_i32_16x16x64_i8 v[94:97], v[66:69], v[210:213], v[94:97]
	v_mfma_i32_16x16x64_i8 v[90:93], v[74:77], v[210:213], v[90:93]
	v_mfma_i32_16x16x64_i8 v[142:145], v[70:73], v[190:193], v[142:145]
	v_mfma_i32_16x16x64_i8 v[138:141], v[78:81], v[190:193], v[138:141]
	v_mfma_i32_16x16x64_i8 v[126:129], v[70:73], v[198:201], v[126:129]
	v_mfma_i32_16x16x64_i8 v[122:125], v[78:81], v[198:201], v[122:125]
	v_mfma_i32_16x16x64_i8 v[110:113], v[70:73], v[206:209], v[110:113]
	v_mfma_i32_16x16x64_i8 v[106:109], v[78:81], v[206:209], v[106:109]
	v_mfma_i32_16x16x64_i8 v[94:97], v[70:73], v[214:217], v[94:97]
	v_mfma_i32_16x16x64_i8 v[90:93], v[78:81], v[214:217], v[90:93]
	v_mfma_i32_16x16x64_i8 v[134:137], v[146:149], v[186:189], v[134:137]
	v_mfma_i32_16x16x64_i8 v[130:133], v[172:175], v[186:189], v[130:133]
	v_mfma_i32_16x16x64_i8 v[118:121], v[146:149], v[194:197], v[118:121]
	v_mfma_i32_16x16x64_i8 v[114:117], v[172:175], v[194:197], v[114:117]
	v_mfma_i32_16x16x64_i8 v[102:105], v[146:149], v[202:205], v[102:105]
	v_mfma_i32_16x16x64_i8 v[98:101], v[172:175], v[202:205], v[98:101]
	v_mfma_i32_16x16x64_i8 v[86:89], v[146:149], v[210:213], v[86:89]
	v_mfma_i32_16x16x64_i8 v[82:85], v[172:175], v[210:213], v[82:85]
	v_mfma_i32_16x16x64_i8 v[134:137], v[150:153], v[190:193], v[134:137]
	v_mfma_i32_16x16x64_i8 v[130:133], v[182:185], v[190:193], v[130:133]
	v_mfma_i32_16x16x64_i8 v[118:121], v[150:153], v[198:201], v[118:121]
	v_mfma_i32_16x16x64_i8 v[114:117], v[182:185], v[198:201], v[114:117]
	v_mfma_i32_16x16x64_i8 v[102:105], v[150:153], v[206:209], v[102:105]
	v_mfma_i32_16x16x64_i8 v[98:101], v[182:185], v[206:209], v[98:101]
	v_mfma_i32_16x16x64_i8 v[86:89], v[150:153], v[214:217], v[86:89]
	v_mfma_i32_16x16x64_i8 v[82:85], v[182:185], v[214:217], v[82:85]
	s_barrier
	s_add_u32 s26, s24, 0x8000
	s_addc_u32 s27, s25, 0
	s_add_i32 s52, s52, s33
	s_mov_b32 m0, s52
	ds_read_b128 v[186:189], v180 offset:49152
	ds_read_b128 v[190:193], v180 offset:50176
	ds_read_b128 v[194:197], v180 offset:51200
	ds_read_b128 v[198:201], v180 offset:52224
	ds_read_b128 v[202:205], v180 offset:53248
	ds_read_b128 v[206:209], v180 offset:54272
	ds_read_b128 v[210:213], v180 offset:55296
	ds_read_b128 v[214:217], v180 offset:56320
	global_load_lds_dwordx4 v156, s[26:27]
	s_add_i32 m0, s52, 0x2000
	s_add_u32 s24, s24, 0xc000
	v_lshl_add_u64 v[218:219], s[26:27], 0, v[160:161]
	s_addc_u32 s25, s25, 0
	s_add_i32 s26, s53, s33
	global_load_lds_dwordx4 v[218:219], off
	s_mov_b32 m0, s26
	s_nop 0
	global_load_lds_dwordx4 v156, s[24:25]
	s_add_i32 m0, s26, 0x2000
	s_nop 0
	global_load_lds_dwordx4 v160, s[24:25]
	s_waitcnt vmcnt(6)
	s_waitcnt lgkmcnt(0)
	s_barrier
	s_waitcnt lgkmcnt(0)
	v_mfma_i32_16x16x64_i8 v[62:65], v[66:69], v[186:189], v[62:65]
	v_mfma_i32_16x16x64_i8 v[58:61], v[74:77], v[186:189], v[58:61]
	v_mfma_i32_16x16x64_i8 v[46:49], v[66:69], v[194:197], v[46:49]
	v_mfma_i32_16x16x64_i8 v[42:45], v[74:77], v[194:197], v[42:45]
	v_mfma_i32_16x16x64_i8 v[30:33], v[66:69], v[202:205], v[30:33]
	v_mfma_i32_16x16x64_i8 v[26:29], v[74:77], v[202:205], v[26:29]
	v_mfma_i32_16x16x64_i8 v[14:17], v[66:69], v[210:213], v[14:17]
	v_mfma_i32_16x16x64_i8 v[10:13], v[74:77], v[210:213], v[10:13]
	v_mfma_i32_16x16x64_i8 v[62:65], v[70:73], v[190:193], v[62:65]
	v_mfma_i32_16x16x64_i8 v[58:61], v[78:81], v[190:193], v[58:61]
	v_mfma_i32_16x16x64_i8 v[46:49], v[70:73], v[198:201], v[46:49]
	v_mfma_i32_16x16x64_i8 v[42:45], v[78:81], v[198:201], v[42:45]
	v_mfma_i32_16x16x64_i8 v[30:33], v[70:73], v[206:209], v[30:33]
	v_mfma_i32_16x16x64_i8 v[26:29], v[78:81], v[206:209], v[26:29]
	v_mfma_i32_16x16x64_i8 v[14:17], v[70:73], v[214:217], v[14:17]
	v_mfma_i32_16x16x64_i8 v[10:13], v[78:81], v[214:217], v[10:13]
	v_mfma_i32_16x16x64_i8 v[54:57], v[146:149], v[186:189], v[54:57]
	v_mfma_i32_16x16x64_i8 v[50:53], v[172:175], v[186:189], v[50:53]
	v_mfma_i32_16x16x64_i8 v[38:41], v[146:149], v[194:197], v[38:41]
	v_mfma_i32_16x16x64_i8 v[34:37], v[172:175], v[194:197], v[34:37]
	v_mfma_i32_16x16x64_i8 v[22:25], v[146:149], v[202:205], v[22:25]
	v_mfma_i32_16x16x64_i8 v[18:21], v[172:175], v[202:205], v[18:21]
	v_mfma_i32_16x16x64_i8 v[6:9], v[146:149], v[210:213], v[6:9]
	v_mfma_i32_16x16x64_i8 v[2:5], v[172:175], v[210:213], v[2:5]
	v_mfma_i32_16x16x64_i8 v[54:57], v[150:153], v[190:193], v[54:57]
	v_mfma_i32_16x16x64_i8 v[50:53], v[182:185], v[190:193], v[50:53]
	v_mfma_i32_16x16x64_i8 v[38:41], v[150:153], v[198:201], v[38:41]
	v_mfma_i32_16x16x64_i8 v[34:37], v[182:185], v[198:201], v[34:37]
	v_mfma_i32_16x16x64_i8 v[22:25], v[150:153], v[206:209], v[22:25]
	v_mfma_i32_16x16x64_i8 v[18:21], v[182:185], v[206:209], v[18:21]
	v_mfma_i32_16x16x64_i8 v[6:9], v[150:153], v[214:217], v[6:9]
	v_mfma_i32_16x16x64_i8 v[2:5], v[182:185], v[214:217], v[2:5]
	s_add_i32 s51, s51, 2
	s_add_u32 s20, s20, 0x10000
	s_addc_u32 s21, s21, 0
	s_add_u32 s49, s49, 0x10000
	s_addc_u32 s50, s50, 0
	s_cmpk_gt_u32 s51, 0x53
	s_barrier
	s_cbranch_scc0 .LBB0_4168
	s_and_b64 vcc, exec, s[14:15]
	s_cbranch_vccz .LBB0_4171
	s_barrier
